# hand-written RW scan consumer (2 rows x 8 cols per lane, LDS prefetch, DPP reduce-scatter); producer unchanged
# speedup vs baseline: 1.0199x; 1.0199x over previous
; DN void rw_scan_item(const Params& p, int l, int item, bool need_ctx, int mode) {
;     ...
;     const int rq = tid >> 4, j16 = tid & 15;
;     f32x2 S[4][2];
; #pragma unroll
;     for (int k = 0; k < 4; ++k) { S[k][0] = (f32x2){0.f, 0.f}; S[k][1] = (f32x2){0.f, 0.f}; }
;     __syncthreads();
; #pragma unroll 1
;     for (int c = 0; c < nchunks; ++c) {
;       const float* vec = lbase + (c & 1) * 7168;
;       const float* vvv = vec + 16 * 5 * 64;
;       float* ybuf = lbase + (c & 1) * 7168 + 16 * 5 * 64 + 16 * 64;
;       if (mode != 1) {
;         float ykeep[4] = {0.f, 0.f, 0.f, 0.f};
; #pragma unroll
;         for (int hb = 0; hb < 2; ++hb) {
;           float yp[4][8];
; #pragma unroll
;           for (int s8 = 0; s8 < 8; ++s8) {
;             const int s = hb * 8 + s8;
;             const float* vs = vec + s * 320 + j16 * 4;
;             const f32x4v w0 = *(const f32x4v*)(vs);
;             const f32x4v d0 = *(const f32x4v*)(vs + 64);
;             const f32x4v a0 = *(const f32x4v*)(vs + 128);
;             const f32x4v b0 = *(const f32x4v*)(vs + 192);
;             const f32x4v q0 = *(const f32x4v*)(vs + 256);
;             float sa[4], vi[4];
; #pragma unroll
;             for (int k = 0; k < 4; ++k) {
;               vi[k] = vvv[s * 64 + rq + 16 * k];
;               f32x2 t = S[k][0] * a0.xy;
;               t = S[k][1] * a0.zw + t;
;               sa[k] = t.x + t.y;
;             }
; #pragma unroll
;             for (int k = 0; k < 4; ++k) sa[k] += dppf<0xB1>(sa[k]);
; #pragma unroll
;             for (int k = 0; k < 4; ++k) sa[k] += dppf<0x4E>(sa[k]);
; #pragma unroll
;             for (int k = 0; k < 4; ++k) sa[k] += dppf<0x141>(sa[k]);
; #pragma unroll
;             for (int k = 0; k < 4; ++k) sa[k] += dppf<0x140>(sa[k]);
; #pragma unroll
;             for (int k = 0; k < 4; ++k) {
;               const f32x2 s2 = (f32x2){sa[k], sa[k]}, v2 = (f32x2){vi[k], vi[k]};
;               S[k][0] = S[k][0] * w0.xy + (s2 * b0.xy + v2 * d0.xy);
;               S[k][1] = S[k][1] * w0.zw + (s2 * b0.zw + v2 * d0.zw);
;               f32x2 y2 = S[k][0] * q0.xy;
;               y2 = S[k][1] * q0.zw + y2;
;               yp[k][s8] = y2.x + y2.y;
;             }
.LBB0_511:
	v_readfirstlane_b32 s2, v182
	s_lshr_b32 s2, s2, 8
	v_mov_b32_e32 v24, v183
	s_cmp_lg_u32 s2, 1
	s_mov_b64 s[2:3], -1
	s_barrier
	s_cbranch_scc0 .LBB0_515
	v_and_b32_e32 v149, 1, v183
	v_and_b32_e32 v150, 2, v183
	v_cmp_ne_u32_e64 s[6:7], 0, v149
	v_cmp_ne_u32_e64 s[8:9], 0, v150
	v_lshlrev_b32_e32 v150, 1, v150
	v_lshl_add_u32 v151, v149, 1, v150
	v_bfe_u32 v149, v183, 2, 1
	v_add_u32_e32 v151, v151, v149
	v_lshrrev_b32_e32 v150, 3, v183
	v_lshlrev_b32_e32 v150, 3, v150
	v_lshl_add_u32 v151, v151, 8, v150
	v_and_b32_e32 v149, 7, v183
	v_lshlrev_b32_e32 v149, 5, v149
	v_mov_b32_e32 v0, 0
	v_mov_b32_e32 v1, 0
	v_mov_b32_e32 v2, 0
	v_mov_b32_e32 v3, 0
	v_mov_b32_e32 v4, 0
	v_mov_b32_e32 v5, 0
	v_mov_b32_e32 v6, 0
	v_mov_b32_e32 v7, 0
	v_mov_b32_e32 v8, 0
	v_mov_b32_e32 v9, 0
	v_mov_b32_e32 v10, 0
	v_mov_b32_e32 v11, 0
	v_mov_b32_e32 v12, 0
	v_mov_b32_e32 v13, 0
	v_mov_b32_e32 v14, 0
	v_mov_b32_e32 v15, 0
	s_mov_b32 s2, 0
	s_barrier
.Lrwc_chunk:
	s_bitcmp1_b32 s2, 0
	s_cselect_b32 s3, 0x7000, 0
	v_add_u32_e32 v58, s3, v149
	v_add_u32_e32 v59, s3, v150
	v_add_u32_e32 v148, s3, v151
	ds_read_b128 v[16:19], v58 offset:512
	ds_read_b128 v[20:23], v58 offset:528
	ds_read_b64 v[56:57], v59 offset:20480
	ds_read_b128 v[24:27], v58 offset:256
	ds_read_b128 v[28:31], v58 offset:272
	ds_read_b128 v[32:35], v58 offset:768
	ds_read_b128 v[36:39], v58 offset:784
	ds_read_b128 v[40:43], v58 offset:0
	ds_read_b128 v[44:47], v58 offset:16
	ds_read_b128 v[48:51], v58 offset:1024
	ds_read_b128 v[52:55], v58 offset:1040
	s_waitcnt lgkmcnt(9)
	v_pk_mul_f32 v[118:119], v[0:1], v[16:17]
	v_pk_mul_f32 v[120:121], v[8:9], v[16:17]
	v_pk_fma_f32 v[118:119], v[2:3], v[18:19], v[118:119]
	v_pk_fma_f32 v[120:121], v[10:11], v[18:19], v[120:121]
	v_pk_fma_f32 v[118:119], v[4:5], v[20:21], v[118:119]
	v_pk_fma_f32 v[120:121], v[12:13], v[20:21], v[120:121]
	v_pk_fma_f32 v[118:119], v[6:7], v[22:23], v[118:119]
	v_pk_fma_f32 v[120:121], v[14:15], v[22:23], v[120:121]
	v_add_f32_e32 v122, v118, v119
	v_add_f32_e32 v123, v120, v121
	s_nop 0
	v_add_f32_dpp v122, v122, v122 quad_perm:[1,0,3,2] row_mask:0xf bank_mask:0xf bound_ctrl:1
	v_add_f32_dpp v123, v123, v123 quad_perm:[1,0,3,2] row_mask:0xf bank_mask:0xf bound_ctrl:1
	s_nop 0
	v_add_f32_dpp v122, v122, v122 quad_perm:[2,3,0,1] row_mask:0xf bank_mask:0xf bound_ctrl:1
	v_add_f32_dpp v123, v123, v123 quad_perm:[2,3,0,1] row_mask:0xf bank_mask:0xf bound_ctrl:1
	s_nop 0
	v_add_f32_dpp v122, v122, v122 row_half_mirror row_mask:0xf bank_mask:0xf bound_ctrl:1
	v_add_f32_dpp v123, v123, v123 row_half_mirror row_mask:0xf bank_mask:0xf bound_ctrl:1
	s_waitcnt lgkmcnt(0)
	ds_read_b128 v[60:63], v58 offset:1792
	v_pk_mul_f32 v[102:103], v[24:25], v[56:57] op_sel_hi:[1,0]
	ds_read_b128 v[64:67], v58 offset:1808
	v_pk_mul_f32 v[110:111], v[24:25], v[56:57] op_sel:[0,1] op_sel_hi:[1,1]
	ds_read_b64 v[100:101], v59 offset:20736
	v_pk_mul_f32 v[104:105], v[26:27], v[56:57] op_sel_hi:[1,0]
	ds_read_b128 v[68:71], v58 offset:1536
	v_pk_mul_f32 v[112:113], v[26:27], v[56:57] op_sel:[0,1] op_sel_hi:[1,1]
	ds_read_b128 v[72:75], v58 offset:1552
	v_pk_mul_f32 v[106:107], v[28:29], v[56:57] op_sel_hi:[1,0]
	ds_read_b128 v[76:79], v58 offset:2048
	v_pk_mul_f32 v[114:115], v[28:29], v[56:57] op_sel:[0,1] op_sel_hi:[1,1]
	ds_read_b128 v[80:83], v58 offset:2064
	v_pk_mul_f32 v[108:109], v[30:31], v[56:57] op_sel_hi:[1,0]
	ds_read_b128 v[84:87], v58 offset:1280
	v_pk_mul_f32 v[116:117], v[30:31], v[56:57] op_sel:[0,1] op_sel_hi:[1,1]
	ds_read_b128 v[88:91], v58 offset:1296
	ds_read_b128 v[92:95], v58 offset:2304
	ds_read_b128 v[96:99], v58 offset:2320
	v_pk_fma_f32 v[102:103], v[32:33], v[122:123], v[102:103] op_sel_hi:[1,0,1]
	v_pk_fma_f32 v[110:111], v[32:33], v[122:123], v[110:111] op_sel:[0,1,0] op_sel_hi:[1,1,1]
	v_pk_fma_f32 v[104:105], v[34:35], v[122:123], v[104:105] op_sel_hi:[1,0,1]
	v_pk_fma_f32 v[112:113], v[34:35], v[122:123], v[112:113] op_sel:[0,1,0] op_sel_hi:[1,1,1]
	v_pk_fma_f32 v[106:107], v[36:37], v[122:123], v[106:107] op_sel_hi:[1,0,1]
	v_pk_fma_f32 v[114:115], v[36:37], v[122:123], v[114:115] op_sel:[0,1,0] op_sel_hi:[1,1,1]
	v_pk_fma_f32 v[108:109], v[38:39], v[122:123], v[108:109] op_sel_hi:[1,0,1]
	v_pk_fma_f32 v[116:117], v[38:39], v[122:123], v[116:117] op_sel:[0,1,0] op_sel_hi:[1,1,1]
	v_pk_fma_f32 v[0:1], v[0:1], v[40:41], v[102:103]
	v_pk_fma_f32 v[8:9], v[8:9], v[40:41], v[110:111]
	v_pk_fma_f32 v[2:3], v[2:3], v[42:43], v[104:105]
	v_pk_fma_f32 v[10:11], v[10:11], v[42:43], v[112:113]
	v_pk_fma_f32 v[4:5], v[4:5], v[44:45], v[106:107]
	v_pk_fma_f32 v[12:13], v[12:13], v[44:45], v[114:115]
	v_pk_fma_f32 v[6:7], v[6:7], v[46:47], v[108:109]
	v_pk_fma_f32 v[14:15], v[14:15], v[46:47], v[116:117]
	s_waitcnt lgkmcnt(9)
	v_pk_mul_f32 v[118:119], v[0:1], v[60:61]
	v_pk_mul_f32 v[120:121], v[8:9], v[60:61]
	v_pk_mul_f32 v[124:125], v[0:1], v[48:49]
	v_pk_fma_f32 v[118:119], v[2:3], v[62:63], v[118:119]
	v_pk_fma_f32 v[120:121], v[10:11], v[62:63], v[120:121]
	v_pk_mul_f32 v[126:127], v[8:9], v[48:49]
	v_pk_fma_f32 v[118:119], v[4:5], v[64:65], v[118:119]
	v_pk_fma_f32 v[120:121], v[12:13], v[64:65], v[120:121]
	v_pk_fma_f32 v[124:125], v[2:3], v[50:51], v[124:125]
	v_pk_fma_f32 v[118:119], v[6:7], v[66:67], v[118:119]
	v_pk_fma_f32 v[120:121], v[14:15], v[66:67], v[120:121]
	v_pk_fma_f32 v[126:127], v[10:11], v[50:51], v[126:127]
	v_add_f32_e32 v122, v118, v119
	v_add_f32_e32 v123, v120, v121
	v_pk_fma_f32 v[124:125], v[4:5], v[52:53], v[124:125]
	v_pk_fma_f32 v[126:127], v[12:13], v[52:53], v[126:127]
	v_add_f32_dpp v122, v122, v122 quad_perm:[1,0,3,2] row_mask:0xf bank_mask:0xf bound_ctrl:1
	v_add_f32_dpp v123, v123, v123 quad_perm:[1,0,3,2] row_mask:0xf bank_mask:0xf bound_ctrl:1
	v_pk_fma_f32 v[124:125], v[6:7], v[54:55], v[124:125]
	v_pk_fma_f32 v[126:127], v[14:15], v[54:55], v[126:127]
	v_add_f32_dpp v122, v122, v122 quad_perm:[2,3,0,1] row_mask:0xf bank_mask:0xf bound_ctrl:1
	v_add_f32_dpp v123, v123, v123 quad_perm:[2,3,0,1] row_mask:0xf bank_mask:0xf bound_ctrl:1
	v_add_f32_e32 v128, v124, v125
	v_add_f32_e32 v130, v126, v127
	v_add_f32_dpp v122, v122, v122 row_half_mirror row_mask:0xf bank_mask:0xf bound_ctrl:1
	v_add_f32_dpp v123, v123, v123 row_half_mirror row_mask:0xf bank_mask:0xf bound_ctrl:1
	s_waitcnt lgkmcnt(0)
; DN void rw_scan_item(const Params& p, int l, int item, bool need_ctx, int mode) {
;     ...
;           for (int s8 = 0; s8 < 8; ++s8) {
;             const int s = hb * 8 + s8;
;             const float* vs = vec + s * 320 + j16 * 4;
;             const f32x4v w0 = *(const f32x4v*)(vs);
;             const f32x4v d0 = *(const f32x4v*)(vs + 64);
;             const f32x4v a0 = *(const f32x4v*)(vs + 128);
;             const f32x4v b0 = *(const f32x4v*)(vs + 192);
;             const f32x4v q0 = *(const f32x4v*)(vs + 256);
;             float sa[4], vi[4];
; #pragma unroll
;             for (int k = 0; k < 4; ++k) {
;               vi[k] = vvv[s * 64 + rq + 16 * k];
;               f32x2 t = S[k][0] * a0.xy;
;               t = S[k][1] * a0.zw + t;
;               sa[k] = t.x + t.y;
;             }
; #pragma unroll
;             for (int k = 0; k < 4; ++k) sa[k] += dppf<0xB1>(sa[k]);
; #pragma unroll
;             for (int k = 0; k < 4; ++k) sa[k] += dppf<0x4E>(sa[k]);
; #pragma unroll
;             for (int k = 0; k < 4; ++k) sa[k] += dppf<0x141>(sa[k]);
; #pragma unroll
;             for (int k = 0; k < 4; ++k) sa[k] += dppf<0x140>(sa[k]);
; #pragma unroll
;             for (int k = 0; k < 4; ++k) {
;               const f32x2 s2 = (f32x2){sa[k], sa[k]}, v2 = (f32x2){vi[k], vi[k]};
;               S[k][0] = S[k][0] * w0.xy + (s2 * b0.xy + v2 * d0.xy);
;               S[k][1] = S[k][1] * w0.zw + (s2 * b0.zw + v2 * d0.zw);
;               f32x2 y2 = S[k][0] * q0.xy;
;               y2 = S[k][1] * q0.zw + y2;
;               yp[k][s8] = y2.x + y2.y;
;             }
;           }
	ds_read_b128 v[16:19], v58 offset:3072
	v_pk_mul_f32 v[102:103], v[68:69], v[100:101] op_sel_hi:[1,0]
	ds_read_b128 v[20:23], v58 offset:3088
	v_pk_mul_f32 v[110:111], v[68:69], v[100:101] op_sel:[0,1] op_sel_hi:[1,1]
	ds_read_b64 v[56:57], v59 offset:20992
	v_pk_mul_f32 v[104:105], v[70:71], v[100:101] op_sel_hi:[1,0]
	ds_read_b128 v[24:27], v58 offset:2816
	v_pk_mul_f32 v[112:113], v[70:71], v[100:101] op_sel:[0,1] op_sel_hi:[1,1]
	ds_read_b128 v[28:31], v58 offset:2832
	v_pk_mul_f32 v[106:107], v[72:73], v[100:101] op_sel_hi:[1,0]
	ds_read_b128 v[32:35], v58 offset:3328
	v_pk_mul_f32 v[114:115], v[72:73], v[100:101] op_sel:[0,1] op_sel_hi:[1,1]
	ds_read_b128 v[36:39], v58 offset:3344
	v_pk_mul_f32 v[108:109], v[74:75], v[100:101] op_sel_hi:[1,0]
	ds_read_b128 v[40:43], v58 offset:2560
	v_pk_mul_f32 v[116:117], v[74:75], v[100:101] op_sel:[0,1] op_sel_hi:[1,1]
	ds_read_b128 v[44:47], v58 offset:2576
	ds_read_b128 v[48:51], v58 offset:3584
	ds_read_b128 v[52:55], v58 offset:3600
	v_pk_fma_f32 v[102:103], v[76:77], v[122:123], v[102:103] op_sel_hi:[1,0,1]
	v_pk_fma_f32 v[110:111], v[76:77], v[122:123], v[110:111] op_sel:[0,1,0] op_sel_hi:[1,1,1]
	v_pk_fma_f32 v[104:105], v[78:79], v[122:123], v[104:105] op_sel_hi:[1,0,1]
	v_pk_fma_f32 v[112:113], v[78:79], v[122:123], v[112:113] op_sel:[0,1,0] op_sel_hi:[1,1,1]
	v_pk_fma_f32 v[106:107], v[80:81], v[122:123], v[106:107] op_sel_hi:[1,0,1]
	v_pk_fma_f32 v[114:115], v[80:81], v[122:123], v[114:115] op_sel:[0,1,0] op_sel_hi:[1,1,1]
	v_pk_fma_f32 v[108:109], v[82:83], v[122:123], v[108:109] op_sel_hi:[1,0,1]
	v_pk_fma_f32 v[116:117], v[82:83], v[122:123], v[116:117] op_sel:[0,1,0] op_sel_hi:[1,1,1]
	v_pk_fma_f32 v[0:1], v[0:1], v[84:85], v[102:103]
	v_pk_fma_f32 v[8:9], v[8:9], v[84:85], v[110:111]
	v_pk_fma_f32 v[2:3], v[2:3], v[86:87], v[104:105]
	v_pk_fma_f32 v[10:11], v[10:11], v[86:87], v[112:113]
	v_pk_fma_f32 v[4:5], v[4:5], v[88:89], v[106:107]
	v_pk_fma_f32 v[12:13], v[12:13], v[88:89], v[114:115]
	v_pk_fma_f32 v[6:7], v[6:7], v[90:91], v[108:109]
	v_pk_fma_f32 v[14:15], v[14:15], v[90:91], v[116:117]
	s_waitcnt lgkmcnt(9)
	v_pk_mul_f32 v[118:119], v[0:1], v[16:17]
	v_pk_mul_f32 v[120:121], v[8:9], v[16:17]
	v_pk_mul_f32 v[124:125], v[0:1], v[92:93]
	v_pk_fma_f32 v[118:119], v[2:3], v[18:19], v[118:119]
	v_pk_fma_f32 v[120:121], v[10:11], v[18:19], v[120:121]
	v_pk_mul_f32 v[126:127], v[8:9], v[92:93]
	v_pk_fma_f32 v[118:119], v[4:5], v[20:21], v[118:119]
	v_pk_fma_f32 v[120:121], v[12:13], v[20:21], v[120:121]
	v_pk_fma_f32 v[124:125], v[2:3], v[94:95], v[124:125]
	v_pk_fma_f32 v[118:119], v[6:7], v[22:23], v[118:119]
	v_pk_fma_f32 v[120:121], v[14:15], v[22:23], v[120:121]
	v_pk_fma_f32 v[126:127], v[10:11], v[94:95], v[126:127]
	v_add_f32_e32 v122, v118, v119
	v_add_f32_e32 v123, v120, v121
	v_pk_fma_f32 v[124:125], v[4:5], v[96:97], v[124:125]
	v_pk_fma_f32 v[126:127], v[12:13], v[96:97], v[126:127]
	v_add_f32_dpp v122, v122, v122 quad_perm:[1,0,3,2] row_mask:0xf bank_mask:0xf bound_ctrl:1
	v_add_f32_dpp v123, v123, v123 quad_perm:[1,0,3,2] row_mask:0xf bank_mask:0xf bound_ctrl:1
	v_pk_fma_f32 v[124:125], v[6:7], v[98:99], v[124:125]
	v_pk_fma_f32 v[126:127], v[14:15], v[98:99], v[126:127]
	v_add_f32_dpp v122, v122, v122 quad_perm:[2,3,0,1] row_mask:0xf bank_mask:0xf bound_ctrl:1
	v_add_f32_dpp v123, v123, v123 quad_perm:[2,3,0,1] row_mask:0xf bank_mask:0xf bound_ctrl:1
	v_add_f32_e32 v129, v124, v125
	v_add_f32_e32 v131, v126, v127
	v_add_f32_dpp v122, v122, v122 row_half_mirror row_mask:0xf bank_mask:0xf bound_ctrl:1
	v_add_f32_dpp v123, v123, v123 row_half_mirror row_mask:0xf bank_mask:0xf bound_ctrl:1
	s_waitcnt lgkmcnt(0)
	ds_read_b128 v[60:63], v58 offset:4352
	v_pk_mul_f32 v[102:103], v[24:25], v[56:57] op_sel_hi:[1,0]
	ds_read_b128 v[64:67], v58 offset:4368
	v_pk_mul_f32 v[110:111], v[24:25], v[56:57] op_sel:[0,1] op_sel_hi:[1,1]
	ds_read_b64 v[100:101], v59 offset:21248
	v_pk_mul_f32 v[104:105], v[26:27], v[56:57] op_sel_hi:[1,0]
	ds_read_b128 v[68:71], v58 offset:4096
	v_pk_mul_f32 v[112:113], v[26:27], v[56:57] op_sel:[0,1] op_sel_hi:[1,1]
	ds_read_b128 v[72:75], v58 offset:4112
	v_pk_mul_f32 v[106:107], v[28:29], v[56:57] op_sel_hi:[1,0]
	ds_read_b128 v[76:79], v58 offset:4608
	v_pk_mul_f32 v[114:115], v[28:29], v[56:57] op_sel:[0,1] op_sel_hi:[1,1]
	ds_read_b128 v[80:83], v58 offset:4624
	v_pk_mul_f32 v[108:109], v[30:31], v[56:57] op_sel_hi:[1,0]
	ds_read_b128 v[84:87], v58 offset:3840
	v_pk_mul_f32 v[116:117], v[30:31], v[56:57] op_sel:[0,1] op_sel_hi:[1,1]
	ds_read_b128 v[88:91], v58 offset:3856
	ds_read_b128 v[92:95], v58 offset:4864
	ds_read_b128 v[96:99], v58 offset:4880
	v_pk_fma_f32 v[102:103], v[32:33], v[122:123], v[102:103] op_sel_hi:[1,0,1]
	v_pk_fma_f32 v[110:111], v[32:33], v[122:123], v[110:111] op_sel:[0,1,0] op_sel_hi:[1,1,1]
	v_add_f32_dpp v132, v128, v128 row_ror:12 row_mask:0xf bank_mask:0x5 bound_ctrl:1
	v_pk_fma_f32 v[104:105], v[34:35], v[122:123], v[104:105] op_sel_hi:[1,0,1]
	v_pk_fma_f32 v[112:113], v[34:35], v[122:123], v[112:113] op_sel:[0,1,0] op_sel_hi:[1,1,1]
	v_add_f32_dpp v132, v129, v129 row_ror:4 row_mask:0xf bank_mask:0xa bound_ctrl:1
	v_pk_fma_f32 v[106:107], v[36:37], v[122:123], v[106:107] op_sel_hi:[1,0,1]
	v_pk_fma_f32 v[114:115], v[36:37], v[122:123], v[114:115] op_sel:[0,1,0] op_sel_hi:[1,1,1]
	v_add_f32_dpp v134, v130, v130 row_ror:12 row_mask:0xf bank_mask:0x5 bound_ctrl:1
	v_pk_fma_f32 v[108:109], v[38:39], v[122:123], v[108:109] op_sel_hi:[1,0,1]
	v_pk_fma_f32 v[116:117], v[38:39], v[122:123], v[116:117] op_sel:[0,1,0] op_sel_hi:[1,1,1]
	v_add_f32_dpp v134, v131, v131 row_ror:4 row_mask:0xf bank_mask:0xa bound_ctrl:1
	v_pk_fma_f32 v[0:1], v[0:1], v[40:41], v[102:103]
	v_pk_fma_f32 v[8:9], v[8:9], v[40:41], v[110:111]
	v_pk_fma_f32 v[2:3], v[2:3], v[42:43], v[104:105]
	v_pk_fma_f32 v[10:11], v[10:11], v[42:43], v[112:113]
	v_pk_fma_f32 v[4:5], v[4:5], v[44:45], v[106:107]
	v_pk_fma_f32 v[12:13], v[12:13], v[44:45], v[114:115]
	v_pk_fma_f32 v[6:7], v[6:7], v[46:47], v[108:109]
	v_pk_fma_f32 v[14:15], v[14:15], v[46:47], v[116:117]
	s_waitcnt lgkmcnt(9)
; DN void rw_scan_item(const Params& p, int l, int item, bool need_ctx, int mode) {
;     ...
;           for (int s8 = 0; s8 < 8; ++s8) {
;             const int s = hb * 8 + s8;
;             const float* vs = vec + s * 320 + j16 * 4;
;             const f32x4v w0 = *(const f32x4v*)(vs);
;             const f32x4v d0 = *(const f32x4v*)(vs + 64);
;             const f32x4v a0 = *(const f32x4v*)(vs + 128);
;             const f32x4v b0 = *(const f32x4v*)(vs + 192);
;             const f32x4v q0 = *(const f32x4v*)(vs + 256);
;             float sa[4], vi[4];
; #pragma unroll
;             for (int k = 0; k < 4; ++k) {
;               vi[k] = vvv[s * 64 + rq + 16 * k];
;               f32x2 t = S[k][0] * a0.xy;
;               t = S[k][1] * a0.zw + t;
;               sa[k] = t.x + t.y;
;             }
; #pragma unroll
;             for (int k = 0; k < 4; ++k) sa[k] += dppf<0xB1>(sa[k]);
; #pragma unroll
;             for (int k = 0; k < 4; ++k) sa[k] += dppf<0x4E>(sa[k]);
; #pragma unroll
;             for (int k = 0; k < 4; ++k) sa[k] += dppf<0x141>(sa[k]);
; #pragma unroll
;             for (int k = 0; k < 4; ++k) sa[k] += dppf<0x140>(sa[k]);
; #pragma unroll
;             for (int k = 0; k < 4; ++k) {
;               const f32x2 s2 = (f32x2){sa[k], sa[k]}, v2 = (f32x2){vi[k], vi[k]};
;               S[k][0] = S[k][0] * w0.xy + (s2 * b0.xy + v2 * d0.xy);
;               S[k][1] = S[k][1] * w0.zw + (s2 * b0.zw + v2 * d0.zw);
;               f32x2 y2 = S[k][0] * q0.xy;
;               y2 = S[k][1] * q0.zw + y2;
;               yp[k][s8] = y2.x + y2.y;
;             }
;           }
	v_pk_mul_f32 v[118:119], v[0:1], v[60:61]
	v_pk_mul_f32 v[120:121], v[8:9], v[60:61]
	v_pk_mul_f32 v[124:125], v[0:1], v[48:49]
	v_pk_fma_f32 v[118:119], v[2:3], v[62:63], v[118:119]
	v_pk_fma_f32 v[120:121], v[10:11], v[62:63], v[120:121]
	v_pk_mul_f32 v[126:127], v[8:9], v[48:49]
	v_pk_fma_f32 v[118:119], v[4:5], v[64:65], v[118:119]
	v_pk_fma_f32 v[120:121], v[12:13], v[64:65], v[120:121]
	v_pk_fma_f32 v[124:125], v[2:3], v[50:51], v[124:125]
	v_pk_fma_f32 v[118:119], v[6:7], v[66:67], v[118:119]
	v_pk_fma_f32 v[120:121], v[14:15], v[66:67], v[120:121]
	v_pk_fma_f32 v[126:127], v[10:11], v[50:51], v[126:127]
	v_add_f32_e32 v122, v118, v119
	v_add_f32_e32 v123, v120, v121
	v_pk_fma_f32 v[124:125], v[4:5], v[52:53], v[124:125]
	v_pk_fma_f32 v[126:127], v[12:13], v[52:53], v[126:127]
	v_add_f32_dpp v122, v122, v122 quad_perm:[1,0,3,2] row_mask:0xf bank_mask:0xf bound_ctrl:1
	v_add_f32_dpp v123, v123, v123 quad_perm:[1,0,3,2] row_mask:0xf bank_mask:0xf bound_ctrl:1
	v_pk_fma_f32 v[124:125], v[6:7], v[54:55], v[124:125]
	v_pk_fma_f32 v[126:127], v[14:15], v[54:55], v[126:127]
	v_add_f32_dpp v122, v122, v122 quad_perm:[2,3,0,1] row_mask:0xf bank_mask:0xf bound_ctrl:1
	v_add_f32_dpp v123, v123, v123 quad_perm:[2,3,0,1] row_mask:0xf bank_mask:0xf bound_ctrl:1
	v_add_f32_e32 v128, v124, v125
	v_add_f32_e32 v130, v126, v127
	v_add_f32_dpp v122, v122, v122 row_half_mirror row_mask:0xf bank_mask:0xf bound_ctrl:1
	v_add_f32_dpp v123, v123, v123 row_half_mirror row_mask:0xf bank_mask:0xf bound_ctrl:1
	s_waitcnt lgkmcnt(0)
	ds_read_b128 v[16:19], v58 offset:5632
	v_pk_mul_f32 v[102:103], v[68:69], v[100:101] op_sel_hi:[1,0]
	ds_read_b128 v[20:23], v58 offset:5648
	v_pk_mul_f32 v[110:111], v[68:69], v[100:101] op_sel:[0,1] op_sel_hi:[1,1]
	ds_read_b64 v[56:57], v59 offset:21504
	v_pk_mul_f32 v[104:105], v[70:71], v[100:101] op_sel_hi:[1,0]
	ds_read_b128 v[24:27], v58 offset:5376
	v_pk_mul_f32 v[112:113], v[70:71], v[100:101] op_sel:[0,1] op_sel_hi:[1,1]
	ds_read_b128 v[28:31], v58 offset:5392
	v_pk_mul_f32 v[106:107], v[72:73], v[100:101] op_sel_hi:[1,0]
	ds_read_b128 v[32:35], v58 offset:5888
	v_pk_mul_f32 v[114:115], v[72:73], v[100:101] op_sel:[0,1] op_sel_hi:[1,1]
	ds_read_b128 v[36:39], v58 offset:5904
	v_pk_mul_f32 v[108:109], v[74:75], v[100:101] op_sel_hi:[1,0]
	ds_read_b128 v[40:43], v58 offset:5120
	v_pk_mul_f32 v[116:117], v[74:75], v[100:101] op_sel:[0,1] op_sel_hi:[1,1]
	ds_read_b128 v[44:47], v58 offset:5136
	ds_read_b128 v[48:51], v58 offset:6144
	ds_read_b128 v[52:55], v58 offset:6160
	v_pk_fma_f32 v[102:103], v[76:77], v[122:123], v[102:103] op_sel_hi:[1,0,1]
	v_pk_fma_f32 v[110:111], v[76:77], v[122:123], v[110:111] op_sel:[0,1,0] op_sel_hi:[1,1,1]
	v_pk_fma_f32 v[104:105], v[78:79], v[122:123], v[104:105] op_sel_hi:[1,0,1]
	v_pk_fma_f32 v[112:113], v[78:79], v[122:123], v[112:113] op_sel:[0,1,0] op_sel_hi:[1,1,1]
	v_pk_fma_f32 v[106:107], v[80:81], v[122:123], v[106:107] op_sel_hi:[1,0,1]
	v_pk_fma_f32 v[114:115], v[80:81], v[122:123], v[114:115] op_sel:[0,1,0] op_sel_hi:[1,1,1]
	v_pk_fma_f32 v[108:109], v[82:83], v[122:123], v[108:109] op_sel_hi:[1,0,1]
	v_pk_fma_f32 v[116:117], v[82:83], v[122:123], v[116:117] op_sel:[0,1,0] op_sel_hi:[1,1,1]
	v_pk_fma_f32 v[0:1], v[0:1], v[84:85], v[102:103]
	v_pk_fma_f32 v[8:9], v[8:9], v[84:85], v[110:111]
	v_pk_fma_f32 v[2:3], v[2:3], v[86:87], v[104:105]
	v_pk_fma_f32 v[10:11], v[10:11], v[86:87], v[112:113]
	v_pk_fma_f32 v[4:5], v[4:5], v[88:89], v[106:107]
	v_pk_fma_f32 v[12:13], v[12:13], v[88:89], v[114:115]
	v_pk_fma_f32 v[6:7], v[6:7], v[90:91], v[108:109]
	v_pk_fma_f32 v[14:15], v[14:15], v[90:91], v[116:117]
	s_waitcnt lgkmcnt(9)
	v_pk_mul_f32 v[118:119], v[0:1], v[16:17]
	v_pk_mul_f32 v[120:121], v[8:9], v[16:17]
	v_pk_mul_f32 v[124:125], v[0:1], v[92:93]
	v_pk_fma_f32 v[118:119], v[2:3], v[18:19], v[118:119]
	v_pk_fma_f32 v[120:121], v[10:11], v[18:19], v[120:121]
	v_pk_mul_f32 v[126:127], v[8:9], v[92:93]
	v_pk_fma_f32 v[118:119], v[4:5], v[20:21], v[118:119]
	v_pk_fma_f32 v[120:121], v[12:13], v[20:21], v[120:121]
	v_pk_fma_f32 v[124:125], v[2:3], v[94:95], v[124:125]
	v_pk_fma_f32 v[118:119], v[6:7], v[22:23], v[118:119]
	v_pk_fma_f32 v[120:121], v[14:15], v[22:23], v[120:121]
	v_pk_fma_f32 v[126:127], v[10:11], v[94:95], v[126:127]
	v_add_f32_e32 v122, v118, v119
	v_add_f32_e32 v123, v120, v121
	v_pk_fma_f32 v[124:125], v[4:5], v[96:97], v[124:125]
	v_pk_fma_f32 v[126:127], v[12:13], v[96:97], v[126:127]
	v_add_f32_dpp v122, v122, v122 quad_perm:[1,0,3,2] row_mask:0xf bank_mask:0xf bound_ctrl:1
	v_add_f32_dpp v123, v123, v123 quad_perm:[1,0,3,2] row_mask:0xf bank_mask:0xf bound_ctrl:1
	v_pk_fma_f32 v[124:125], v[6:7], v[98:99], v[124:125]
	v_pk_fma_f32 v[126:127], v[14:15], v[98:99], v[126:127]
	v_add_f32_dpp v122, v122, v122 quad_perm:[2,3,0,1] row_mask:0xf bank_mask:0xf bound_ctrl:1
	v_add_f32_dpp v123, v123, v123 quad_perm:[2,3,0,1] row_mask:0xf bank_mask:0xf bound_ctrl:1
	v_add_f32_e32 v129, v124, v125
	v_add_f32_e32 v131, v126, v127
	v_add_f32_dpp v122, v122, v122 row_half_mirror row_mask:0xf bank_mask:0xf bound_ctrl:1
	v_add_f32_dpp v123, v123, v123 row_half_mirror row_mask:0xf bank_mask:0xf bound_ctrl:1
	s_waitcnt lgkmcnt(0)
; DN void rw_scan_item(const Params& p, int l, int item, bool need_ctx, int mode) {
;     ...
;           for (int s8 = 0; s8 < 8; ++s8) {
;             const int s = hb * 8 + s8;
;             const float* vs = vec + s * 320 + j16 * 4;
;             const f32x4v w0 = *(const f32x4v*)(vs);
;             const f32x4v d0 = *(const f32x4v*)(vs + 64);
;             const f32x4v a0 = *(const f32x4v*)(vs + 128);
;             const f32x4v b0 = *(const f32x4v*)(vs + 192);
;             const f32x4v q0 = *(const f32x4v*)(vs + 256);
;             float sa[4], vi[4];
; #pragma unroll
;             for (int k = 0; k < 4; ++k) {
;               vi[k] = vvv[s * 64 + rq + 16 * k];
;               f32x2 t = S[k][0] * a0.xy;
;               t = S[k][1] * a0.zw + t;
;               sa[k] = t.x + t.y;
;             }
; #pragma unroll
;             for (int k = 0; k < 4; ++k) sa[k] += dppf<0xB1>(sa[k]);
; #pragma unroll
;             for (int k = 0; k < 4; ++k) sa[k] += dppf<0x4E>(sa[k]);
; #pragma unroll
;             for (int k = 0; k < 4; ++k) sa[k] += dppf<0x141>(sa[k]);
; #pragma unroll
;             for (int k = 0; k < 4; ++k) sa[k] += dppf<0x140>(sa[k]);
; #pragma unroll
;             for (int k = 0; k < 4; ++k) {
;               const f32x2 s2 = (f32x2){sa[k], sa[k]}, v2 = (f32x2){vi[k], vi[k]};
;               S[k][0] = S[k][0] * w0.xy + (s2 * b0.xy + v2 * d0.xy);
;               S[k][1] = S[k][1] * w0.zw + (s2 * b0.zw + v2 * d0.zw);
;               f32x2 y2 = S[k][0] * q0.xy;
;               y2 = S[k][1] * q0.zw + y2;
;               yp[k][s8] = y2.x + y2.y;
;             }
;           }
	ds_read_b128 v[60:63], v58 offset:6912
	v_pk_mul_f32 v[102:103], v[24:25], v[56:57] op_sel_hi:[1,0]
	ds_read_b128 v[64:67], v58 offset:6928
	v_pk_mul_f32 v[110:111], v[24:25], v[56:57] op_sel:[0,1] op_sel_hi:[1,1]
	ds_read_b64 v[100:101], v59 offset:21760
	v_pk_mul_f32 v[104:105], v[26:27], v[56:57] op_sel_hi:[1,0]
	ds_read_b128 v[68:71], v58 offset:6656
	v_pk_mul_f32 v[112:113], v[26:27], v[56:57] op_sel:[0,1] op_sel_hi:[1,1]
	ds_read_b128 v[72:75], v58 offset:6672
	v_pk_mul_f32 v[106:107], v[28:29], v[56:57] op_sel_hi:[1,0]
	ds_read_b128 v[76:79], v58 offset:7168
	v_pk_mul_f32 v[114:115], v[28:29], v[56:57] op_sel:[0,1] op_sel_hi:[1,1]
	ds_read_b128 v[80:83], v58 offset:7184
	v_pk_mul_f32 v[108:109], v[30:31], v[56:57] op_sel_hi:[1,0]
	ds_read_b128 v[84:87], v58 offset:6400
	v_pk_mul_f32 v[116:117], v[30:31], v[56:57] op_sel:[0,1] op_sel_hi:[1,1]
	ds_read_b128 v[88:91], v58 offset:6416
	ds_read_b128 v[92:95], v58 offset:7424
	ds_read_b128 v[96:99], v58 offset:7440
	v_pk_fma_f32 v[102:103], v[32:33], v[122:123], v[102:103] op_sel_hi:[1,0,1]
	v_pk_fma_f32 v[110:111], v[32:33], v[122:123], v[110:111] op_sel:[0,1,0] op_sel_hi:[1,1,1]
	v_add_f32_dpp v133, v128, v128 row_ror:12 row_mask:0xf bank_mask:0x5 bound_ctrl:1
	v_pk_fma_f32 v[104:105], v[34:35], v[122:123], v[104:105] op_sel_hi:[1,0,1]
	v_pk_fma_f32 v[112:113], v[34:35], v[122:123], v[112:113] op_sel:[0,1,0] op_sel_hi:[1,1,1]
	v_add_f32_dpp v133, v129, v129 row_ror:4 row_mask:0xf bank_mask:0xa bound_ctrl:1
	v_pk_fma_f32 v[106:107], v[36:37], v[122:123], v[106:107] op_sel_hi:[1,0,1]
	v_pk_fma_f32 v[114:115], v[36:37], v[122:123], v[114:115] op_sel:[0,1,0] op_sel_hi:[1,1,1]
	v_add_f32_dpp v135, v130, v130 row_ror:12 row_mask:0xf bank_mask:0x5 bound_ctrl:1
	v_pk_fma_f32 v[108:109], v[38:39], v[122:123], v[108:109] op_sel_hi:[1,0,1]
	v_pk_fma_f32 v[116:117], v[38:39], v[122:123], v[116:117] op_sel:[0,1,0] op_sel_hi:[1,1,1]
	v_add_f32_dpp v135, v131, v131 row_ror:4 row_mask:0xf bank_mask:0xa bound_ctrl:1
	v_pk_fma_f32 v[0:1], v[0:1], v[40:41], v[102:103]
	v_pk_fma_f32 v[8:9], v[8:9], v[40:41], v[110:111]
	v_cndmask_b32_e64 v140, v132, v133, s[6:7]
	v_pk_fma_f32 v[2:3], v[2:3], v[42:43], v[104:105]
	v_pk_fma_f32 v[10:11], v[10:11], v[42:43], v[112:113]
	v_cndmask_b32_e64 v141, v133, v132, s[6:7]
	v_pk_fma_f32 v[4:5], v[4:5], v[44:45], v[106:107]
	v_pk_fma_f32 v[12:13], v[12:13], v[44:45], v[114:115]
	v_cndmask_b32_e64 v142, v134, v135, s[6:7]
	v_pk_fma_f32 v[6:7], v[6:7], v[46:47], v[108:109]
	v_pk_fma_f32 v[14:15], v[14:15], v[46:47], v[116:117]
	v_cndmask_b32_e64 v143, v135, v134, s[6:7]
	v_add_f32_dpp v136, v141, v140 quad_perm:[1,0,3,2] row_mask:0xf bank_mask:0xf bound_ctrl:1
	s_nop 0
	v_add_f32_dpp v138, v143, v142 quad_perm:[1,0,3,2] row_mask:0xf bank_mask:0xf bound_ctrl:1
	s_waitcnt lgkmcnt(9)
	v_pk_mul_f32 v[118:119], v[0:1], v[60:61]
	v_pk_mul_f32 v[120:121], v[8:9], v[60:61]
	v_pk_mul_f32 v[124:125], v[0:1], v[48:49]
	v_pk_fma_f32 v[118:119], v[2:3], v[62:63], v[118:119]
	v_pk_fma_f32 v[120:121], v[10:11], v[62:63], v[120:121]
	v_pk_mul_f32 v[126:127], v[8:9], v[48:49]
	v_pk_fma_f32 v[118:119], v[4:5], v[64:65], v[118:119]
	v_pk_fma_f32 v[120:121], v[12:13], v[64:65], v[120:121]
	v_pk_fma_f32 v[124:125], v[2:3], v[50:51], v[124:125]
	v_pk_fma_f32 v[118:119], v[6:7], v[66:67], v[118:119]
	v_pk_fma_f32 v[120:121], v[14:15], v[66:67], v[120:121]
	v_pk_fma_f32 v[126:127], v[10:11], v[50:51], v[126:127]
	v_add_f32_e32 v122, v118, v119
	v_add_f32_e32 v123, v120, v121
	v_pk_fma_f32 v[124:125], v[4:5], v[52:53], v[124:125]
	v_pk_fma_f32 v[126:127], v[12:13], v[52:53], v[126:127]
	v_add_f32_dpp v122, v122, v122 quad_perm:[1,0,3,2] row_mask:0xf bank_mask:0xf bound_ctrl:1
	v_add_f32_dpp v123, v123, v123 quad_perm:[1,0,3,2] row_mask:0xf bank_mask:0xf bound_ctrl:1
	v_pk_fma_f32 v[124:125], v[6:7], v[54:55], v[124:125]
	v_pk_fma_f32 v[126:127], v[14:15], v[54:55], v[126:127]
	v_add_f32_dpp v122, v122, v122 quad_perm:[2,3,0,1] row_mask:0xf bank_mask:0xf bound_ctrl:1
	v_add_f32_dpp v123, v123, v123 quad_perm:[2,3,0,1] row_mask:0xf bank_mask:0xf bound_ctrl:1
	v_add_f32_e32 v128, v124, v125
	v_add_f32_e32 v130, v126, v127
	v_add_f32_dpp v122, v122, v122 row_half_mirror row_mask:0xf bank_mask:0xf bound_ctrl:1
	v_add_f32_dpp v123, v123, v123 row_half_mirror row_mask:0xf bank_mask:0xf bound_ctrl:1
	s_waitcnt lgkmcnt(0)
	ds_read_b128 v[16:19], v58 offset:8192
	v_pk_mul_f32 v[102:103], v[68:69], v[100:101] op_sel_hi:[1,0]
	ds_read_b128 v[20:23], v58 offset:8208
	v_pk_mul_f32 v[110:111], v[68:69], v[100:101] op_sel:[0,1] op_sel_hi:[1,1]
	ds_read_b64 v[56:57], v59 offset:22016
	v_pk_mul_f32 v[104:105], v[70:71], v[100:101] op_sel_hi:[1,0]
	ds_read_b128 v[24:27], v58 offset:7936
	v_pk_mul_f32 v[112:113], v[70:71], v[100:101] op_sel:[0,1] op_sel_hi:[1,1]
	ds_read_b128 v[28:31], v58 offset:7952
	v_pk_mul_f32 v[106:107], v[72:73], v[100:101] op_sel_hi:[1,0]
	ds_read_b128 v[32:35], v58 offset:8448
	v_pk_mul_f32 v[114:115], v[72:73], v[100:101] op_sel:[0,1] op_sel_hi:[1,1]
	ds_read_b128 v[36:39], v58 offset:8464
	v_pk_mul_f32 v[108:109], v[74:75], v[100:101] op_sel_hi:[1,0]
	ds_read_b128 v[40:43], v58 offset:7680
	v_pk_mul_f32 v[116:117], v[74:75], v[100:101] op_sel:[0,1] op_sel_hi:[1,1]
	ds_read_b128 v[44:47], v58 offset:7696
	ds_read_b128 v[48:51], v58 offset:8704
	ds_read_b128 v[52:55], v58 offset:8720
	v_pk_fma_f32 v[102:103], v[76:77], v[122:123], v[102:103] op_sel_hi:[1,0,1]
	v_pk_fma_f32 v[110:111], v[76:77], v[122:123], v[110:111] op_sel:[0,1,0] op_sel_hi:[1,1,1]
	v_pk_fma_f32 v[104:105], v[78:79], v[122:123], v[104:105] op_sel_hi:[1,0,1]
	v_pk_fma_f32 v[112:113], v[78:79], v[122:123], v[112:113] op_sel:[0,1,0] op_sel_hi:[1,1,1]
	v_pk_fma_f32 v[106:107], v[80:81], v[122:123], v[106:107] op_sel_hi:[1,0,1]
	v_pk_fma_f32 v[114:115], v[80:81], v[122:123], v[114:115] op_sel:[0,1,0] op_sel_hi:[1,1,1]
	v_pk_fma_f32 v[108:109], v[82:83], v[122:123], v[108:109] op_sel_hi:[1,0,1]
	v_pk_fma_f32 v[116:117], v[82:83], v[122:123], v[116:117] op_sel:[0,1,0] op_sel_hi:[1,1,1]
	v_pk_fma_f32 v[0:1], v[0:1], v[84:85], v[102:103]
	v_pk_fma_f32 v[8:9], v[8:9], v[84:85], v[110:111]
	v_pk_fma_f32 v[2:3], v[2:3], v[86:87], v[104:105]
	v_pk_fma_f32 v[10:11], v[10:11], v[86:87], v[112:113]
	v_pk_fma_f32 v[4:5], v[4:5], v[88:89], v[106:107]
	v_pk_fma_f32 v[12:13], v[12:13], v[88:89], v[114:115]
	v_pk_fma_f32 v[6:7], v[6:7], v[90:91], v[108:109]
	v_pk_fma_f32 v[14:15], v[14:15], v[90:91], v[116:117]
	s_waitcnt lgkmcnt(9)
; DN void rw_scan_item(const Params& p, int l, int item, bool need_ctx, int mode) {
;     ...
;           for (int s8 = 0; s8 < 8; ++s8) {
;             const int s = hb * 8 + s8;
;             const float* vs = vec + s * 320 + j16 * 4;
;             const f32x4v w0 = *(const f32x4v*)(vs);
;             const f32x4v d0 = *(const f32x4v*)(vs + 64);
;             const f32x4v a0 = *(const f32x4v*)(vs + 128);
;             const f32x4v b0 = *(const f32x4v*)(vs + 192);
;             const f32x4v q0 = *(const f32x4v*)(vs + 256);
;             float sa[4], vi[4];
; #pragma unroll
;             for (int k = 0; k < 4; ++k) {
;               vi[k] = vvv[s * 64 + rq + 16 * k];
;               f32x2 t = S[k][0] * a0.xy;
;               t = S[k][1] * a0.zw + t;
;               sa[k] = t.x + t.y;
;             }
; #pragma unroll
;             for (int k = 0; k < 4; ++k) sa[k] += dppf<0xB1>(sa[k]);
; #pragma unroll
;             for (int k = 0; k < 4; ++k) sa[k] += dppf<0x4E>(sa[k]);
; #pragma unroll
;             for (int k = 0; k < 4; ++k) sa[k] += dppf<0x141>(sa[k]);
; #pragma unroll
;             for (int k = 0; k < 4; ++k) sa[k] += dppf<0x140>(sa[k]);
; #pragma unroll
;             for (int k = 0; k < 4; ++k) {
;               const f32x2 s2 = (f32x2){sa[k], sa[k]}, v2 = (f32x2){vi[k], vi[k]};
;               S[k][0] = S[k][0] * w0.xy + (s2 * b0.xy + v2 * d0.xy);
;               S[k][1] = S[k][1] * w0.zw + (s2 * b0.zw + v2 * d0.zw);
;               f32x2 y2 = S[k][0] * q0.xy;
;               y2 = S[k][1] * q0.zw + y2;
;               yp[k][s8] = y2.x + y2.y;
;             }
;           }
	v_pk_mul_f32 v[118:119], v[0:1], v[16:17]
	v_pk_mul_f32 v[120:121], v[8:9], v[16:17]
	v_pk_mul_f32 v[124:125], v[0:1], v[92:93]
	v_pk_fma_f32 v[118:119], v[2:3], v[18:19], v[118:119]
	v_pk_fma_f32 v[120:121], v[10:11], v[18:19], v[120:121]
	v_pk_mul_f32 v[126:127], v[8:9], v[92:93]
	v_pk_fma_f32 v[118:119], v[4:5], v[20:21], v[118:119]
	v_pk_fma_f32 v[120:121], v[12:13], v[20:21], v[120:121]
	v_pk_fma_f32 v[124:125], v[2:3], v[94:95], v[124:125]
	v_pk_fma_f32 v[118:119], v[6:7], v[22:23], v[118:119]
	v_pk_fma_f32 v[120:121], v[14:15], v[22:23], v[120:121]
	v_pk_fma_f32 v[126:127], v[10:11], v[94:95], v[126:127]
	v_add_f32_e32 v122, v118, v119
	v_add_f32_e32 v123, v120, v121
	v_pk_fma_f32 v[124:125], v[4:5], v[96:97], v[124:125]
	v_pk_fma_f32 v[126:127], v[12:13], v[96:97], v[126:127]
	v_add_f32_dpp v122, v122, v122 quad_perm:[1,0,3,2] row_mask:0xf bank_mask:0xf bound_ctrl:1
	v_add_f32_dpp v123, v123, v123 quad_perm:[1,0,3,2] row_mask:0xf bank_mask:0xf bound_ctrl:1
	v_pk_fma_f32 v[124:125], v[6:7], v[98:99], v[124:125]
	v_pk_fma_f32 v[126:127], v[14:15], v[98:99], v[126:127]
	v_add_f32_dpp v122, v122, v122 quad_perm:[2,3,0,1] row_mask:0xf bank_mask:0xf bound_ctrl:1
	v_add_f32_dpp v123, v123, v123 quad_perm:[2,3,0,1] row_mask:0xf bank_mask:0xf bound_ctrl:1
	v_add_f32_e32 v129, v124, v125
	v_add_f32_e32 v131, v126, v127
	v_add_f32_dpp v122, v122, v122 row_half_mirror row_mask:0xf bank_mask:0xf bound_ctrl:1
	v_add_f32_dpp v123, v123, v123 row_half_mirror row_mask:0xf bank_mask:0xf bound_ctrl:1
	s_waitcnt lgkmcnt(0)
	ds_read_b128 v[60:63], v58 offset:9472
	v_pk_mul_f32 v[102:103], v[24:25], v[56:57] op_sel_hi:[1,0]
	ds_read_b128 v[64:67], v58 offset:9488
	v_pk_mul_f32 v[110:111], v[24:25], v[56:57] op_sel:[0,1] op_sel_hi:[1,1]
	ds_read_b64 v[100:101], v59 offset:22272
	v_pk_mul_f32 v[104:105], v[26:27], v[56:57] op_sel_hi:[1,0]
	ds_read_b128 v[68:71], v58 offset:9216
	v_pk_mul_f32 v[112:113], v[26:27], v[56:57] op_sel:[0,1] op_sel_hi:[1,1]
	ds_read_b128 v[72:75], v58 offset:9232
	v_pk_mul_f32 v[106:107], v[28:29], v[56:57] op_sel_hi:[1,0]
	ds_read_b128 v[76:79], v58 offset:9728
	v_pk_mul_f32 v[114:115], v[28:29], v[56:57] op_sel:[0,1] op_sel_hi:[1,1]
	ds_read_b128 v[80:83], v58 offset:9744
	v_pk_mul_f32 v[108:109], v[30:31], v[56:57] op_sel_hi:[1,0]
	ds_read_b128 v[84:87], v58 offset:8960
	v_pk_mul_f32 v[116:117], v[30:31], v[56:57] op_sel:[0,1] op_sel_hi:[1,1]
	ds_read_b128 v[88:91], v58 offset:8976
	ds_read_b128 v[92:95], v58 offset:9984
	ds_read_b128 v[96:99], v58 offset:10000
	v_pk_fma_f32 v[102:103], v[32:33], v[122:123], v[102:103] op_sel_hi:[1,0,1]
	v_pk_fma_f32 v[110:111], v[32:33], v[122:123], v[110:111] op_sel:[0,1,0] op_sel_hi:[1,1,1]
	v_add_f32_dpp v132, v128, v128 row_ror:12 row_mask:0xf bank_mask:0x5 bound_ctrl:1
	v_pk_fma_f32 v[104:105], v[34:35], v[122:123], v[104:105] op_sel_hi:[1,0,1]
	v_pk_fma_f32 v[112:113], v[34:35], v[122:123], v[112:113] op_sel:[0,1,0] op_sel_hi:[1,1,1]
	v_add_f32_dpp v132, v129, v129 row_ror:4 row_mask:0xf bank_mask:0xa bound_ctrl:1
	v_pk_fma_f32 v[106:107], v[36:37], v[122:123], v[106:107] op_sel_hi:[1,0,1]
	v_pk_fma_f32 v[114:115], v[36:37], v[122:123], v[114:115] op_sel:[0,1,0] op_sel_hi:[1,1,1]
	v_add_f32_dpp v134, v130, v130 row_ror:12 row_mask:0xf bank_mask:0x5 bound_ctrl:1
	v_pk_fma_f32 v[108:109], v[38:39], v[122:123], v[108:109] op_sel_hi:[1,0,1]
	v_pk_fma_f32 v[116:117], v[38:39], v[122:123], v[116:117] op_sel:[0,1,0] op_sel_hi:[1,1,1]
	v_add_f32_dpp v134, v131, v131 row_ror:4 row_mask:0xf bank_mask:0xa bound_ctrl:1
	v_pk_fma_f32 v[0:1], v[0:1], v[40:41], v[102:103]
	v_pk_fma_f32 v[8:9], v[8:9], v[40:41], v[110:111]
	v_pk_fma_f32 v[2:3], v[2:3], v[42:43], v[104:105]
	v_pk_fma_f32 v[10:11], v[10:11], v[42:43], v[112:113]
	v_pk_fma_f32 v[4:5], v[4:5], v[44:45], v[106:107]
	v_pk_fma_f32 v[12:13], v[12:13], v[44:45], v[114:115]
	v_pk_fma_f32 v[6:7], v[6:7], v[46:47], v[108:109]
	v_pk_fma_f32 v[14:15], v[14:15], v[46:47], v[116:117]
	s_waitcnt lgkmcnt(9)
	v_pk_mul_f32 v[118:119], v[0:1], v[60:61]
	v_pk_mul_f32 v[120:121], v[8:9], v[60:61]
	v_pk_mul_f32 v[124:125], v[0:1], v[48:49]
	v_pk_fma_f32 v[118:119], v[2:3], v[62:63], v[118:119]
	v_pk_fma_f32 v[120:121], v[10:11], v[62:63], v[120:121]
	v_pk_mul_f32 v[126:127], v[8:9], v[48:49]
	v_pk_fma_f32 v[118:119], v[4:5], v[64:65], v[118:119]
	v_pk_fma_f32 v[120:121], v[12:13], v[64:65], v[120:121]
	v_pk_fma_f32 v[124:125], v[2:3], v[50:51], v[124:125]
	v_pk_fma_f32 v[118:119], v[6:7], v[66:67], v[118:119]
	v_pk_fma_f32 v[120:121], v[14:15], v[66:67], v[120:121]
	v_pk_fma_f32 v[126:127], v[10:11], v[50:51], v[126:127]
	v_add_f32_e32 v122, v118, v119
	v_add_f32_e32 v123, v120, v121
	v_pk_fma_f32 v[124:125], v[4:5], v[52:53], v[124:125]
	v_pk_fma_f32 v[126:127], v[12:13], v[52:53], v[126:127]
	v_add_f32_dpp v122, v122, v122 quad_perm:[1,0,3,2] row_mask:0xf bank_mask:0xf bound_ctrl:1
	v_add_f32_dpp v123, v123, v123 quad_perm:[1,0,3,2] row_mask:0xf bank_mask:0xf bound_ctrl:1
	v_pk_fma_f32 v[124:125], v[6:7], v[54:55], v[124:125]
	v_pk_fma_f32 v[126:127], v[14:15], v[54:55], v[126:127]
	v_add_f32_dpp v122, v122, v122 quad_perm:[2,3,0,1] row_mask:0xf bank_mask:0xf bound_ctrl:1
	v_add_f32_dpp v123, v123, v123 quad_perm:[2,3,0,1] row_mask:0xf bank_mask:0xf bound_ctrl:1
	v_add_f32_e32 v128, v124, v125
	v_add_f32_e32 v130, v126, v127
	v_add_f32_dpp v122, v122, v122 row_half_mirror row_mask:0xf bank_mask:0xf bound_ctrl:1
	v_add_f32_dpp v123, v123, v123 row_half_mirror row_mask:0xf bank_mask:0xf bound_ctrl:1
	s_waitcnt lgkmcnt(0)
; DN void rw_scan_item(const Params& p, int l, int item, bool need_ctx, int mode) {
;     ...
;           for (int s8 = 0; s8 < 8; ++s8) {
;             const int s = hb * 8 + s8;
;             const float* vs = vec + s * 320 + j16 * 4;
;             const f32x4v w0 = *(const f32x4v*)(vs);
;             const f32x4v d0 = *(const f32x4v*)(vs + 64);
;             const f32x4v a0 = *(const f32x4v*)(vs + 128);
;             const f32x4v b0 = *(const f32x4v*)(vs + 192);
;             const f32x4v q0 = *(const f32x4v*)(vs + 256);
;             float sa[4], vi[4];
; #pragma unroll
;             for (int k = 0; k < 4; ++k) {
;               vi[k] = vvv[s * 64 + rq + 16 * k];
;               f32x2 t = S[k][0] * a0.xy;
;               t = S[k][1] * a0.zw + t;
;               sa[k] = t.x + t.y;
;             }
; #pragma unroll
;             for (int k = 0; k < 4; ++k) sa[k] += dppf<0xB1>(sa[k]);
; #pragma unroll
;             for (int k = 0; k < 4; ++k) sa[k] += dppf<0x4E>(sa[k]);
; #pragma unroll
;             for (int k = 0; k < 4; ++k) sa[k] += dppf<0x141>(sa[k]);
; #pragma unroll
;             for (int k = 0; k < 4; ++k) sa[k] += dppf<0x140>(sa[k]);
; #pragma unroll
;             for (int k = 0; k < 4; ++k) {
;               const f32x2 s2 = (f32x2){sa[k], sa[k]}, v2 = (f32x2){vi[k], vi[k]};
;               S[k][0] = S[k][0] * w0.xy + (s2 * b0.xy + v2 * d0.xy);
;               S[k][1] = S[k][1] * w0.zw + (s2 * b0.zw + v2 * d0.zw);
;               f32x2 y2 = S[k][0] * q0.xy;
;               y2 = S[k][1] * q0.zw + y2;
;               yp[k][s8] = y2.x + y2.y;
;             }
;           }
	ds_read_b128 v[16:19], v58 offset:10752
	v_pk_mul_f32 v[102:103], v[68:69], v[100:101] op_sel_hi:[1,0]
	ds_read_b128 v[20:23], v58 offset:10768
	v_pk_mul_f32 v[110:111], v[68:69], v[100:101] op_sel:[0,1] op_sel_hi:[1,1]
	ds_read_b64 v[56:57], v59 offset:22528
	v_pk_mul_f32 v[104:105], v[70:71], v[100:101] op_sel_hi:[1,0]
	ds_read_b128 v[24:27], v58 offset:10496
	v_pk_mul_f32 v[112:113], v[70:71], v[100:101] op_sel:[0,1] op_sel_hi:[1,1]
	ds_read_b128 v[28:31], v58 offset:10512
	v_pk_mul_f32 v[106:107], v[72:73], v[100:101] op_sel_hi:[1,0]
	ds_read_b128 v[32:35], v58 offset:11008
	v_pk_mul_f32 v[114:115], v[72:73], v[100:101] op_sel:[0,1] op_sel_hi:[1,1]
	ds_read_b128 v[36:39], v58 offset:11024
	v_pk_mul_f32 v[108:109], v[74:75], v[100:101] op_sel_hi:[1,0]
	ds_read_b128 v[40:43], v58 offset:10240
	v_pk_mul_f32 v[116:117], v[74:75], v[100:101] op_sel:[0,1] op_sel_hi:[1,1]
	ds_read_b128 v[44:47], v58 offset:10256
	ds_read_b128 v[48:51], v58 offset:11264
	ds_read_b128 v[52:55], v58 offset:11280
	v_pk_fma_f32 v[102:103], v[76:77], v[122:123], v[102:103] op_sel_hi:[1,0,1]
	v_pk_fma_f32 v[110:111], v[76:77], v[122:123], v[110:111] op_sel:[0,1,0] op_sel_hi:[1,1,1]
	v_pk_fma_f32 v[104:105], v[78:79], v[122:123], v[104:105] op_sel_hi:[1,0,1]
	v_pk_fma_f32 v[112:113], v[78:79], v[122:123], v[112:113] op_sel:[0,1,0] op_sel_hi:[1,1,1]
	v_pk_fma_f32 v[106:107], v[80:81], v[122:123], v[106:107] op_sel_hi:[1,0,1]
	v_pk_fma_f32 v[114:115], v[80:81], v[122:123], v[114:115] op_sel:[0,1,0] op_sel_hi:[1,1,1]
	v_pk_fma_f32 v[108:109], v[82:83], v[122:123], v[108:109] op_sel_hi:[1,0,1]
	v_pk_fma_f32 v[116:117], v[82:83], v[122:123], v[116:117] op_sel:[0,1,0] op_sel_hi:[1,1,1]
	v_pk_fma_f32 v[0:1], v[0:1], v[84:85], v[102:103]
	v_pk_fma_f32 v[8:9], v[8:9], v[84:85], v[110:111]
	v_pk_fma_f32 v[2:3], v[2:3], v[86:87], v[104:105]
	v_pk_fma_f32 v[10:11], v[10:11], v[86:87], v[112:113]
	v_pk_fma_f32 v[4:5], v[4:5], v[88:89], v[106:107]
	v_pk_fma_f32 v[12:13], v[12:13], v[88:89], v[114:115]
	v_pk_fma_f32 v[6:7], v[6:7], v[90:91], v[108:109]
	v_pk_fma_f32 v[14:15], v[14:15], v[90:91], v[116:117]
	s_waitcnt lgkmcnt(9)
	v_pk_mul_f32 v[118:119], v[0:1], v[16:17]
	v_pk_mul_f32 v[120:121], v[8:9], v[16:17]
	v_pk_mul_f32 v[124:125], v[0:1], v[92:93]
	v_pk_fma_f32 v[118:119], v[2:3], v[18:19], v[118:119]
	v_pk_fma_f32 v[120:121], v[10:11], v[18:19], v[120:121]
	v_pk_mul_f32 v[126:127], v[8:9], v[92:93]
	v_pk_fma_f32 v[118:119], v[4:5], v[20:21], v[118:119]
	v_pk_fma_f32 v[120:121], v[12:13], v[20:21], v[120:121]
	v_pk_fma_f32 v[124:125], v[2:3], v[94:95], v[124:125]
	v_pk_fma_f32 v[118:119], v[6:7], v[22:23], v[118:119]
	v_pk_fma_f32 v[120:121], v[14:15], v[22:23], v[120:121]
	v_pk_fma_f32 v[126:127], v[10:11], v[94:95], v[126:127]
	v_add_f32_e32 v122, v118, v119
	v_add_f32_e32 v123, v120, v121
	v_pk_fma_f32 v[124:125], v[4:5], v[96:97], v[124:125]
	v_pk_fma_f32 v[126:127], v[12:13], v[96:97], v[126:127]
	v_add_f32_dpp v122, v122, v122 quad_perm:[1,0,3,2] row_mask:0xf bank_mask:0xf bound_ctrl:1
	v_add_f32_dpp v123, v123, v123 quad_perm:[1,0,3,2] row_mask:0xf bank_mask:0xf bound_ctrl:1
	v_pk_fma_f32 v[124:125], v[6:7], v[98:99], v[124:125]
	v_pk_fma_f32 v[126:127], v[14:15], v[98:99], v[126:127]
	v_add_f32_dpp v122, v122, v122 quad_perm:[2,3,0,1] row_mask:0xf bank_mask:0xf bound_ctrl:1
	v_add_f32_dpp v123, v123, v123 quad_perm:[2,3,0,1] row_mask:0xf bank_mask:0xf bound_ctrl:1
	v_add_f32_e32 v129, v124, v125
	v_add_f32_e32 v131, v126, v127
	v_add_f32_dpp v122, v122, v122 row_half_mirror row_mask:0xf bank_mask:0xf bound_ctrl:1
	v_add_f32_dpp v123, v123, v123 row_half_mirror row_mask:0xf bank_mask:0xf bound_ctrl:1
	s_waitcnt lgkmcnt(0)
	ds_read_b128 v[60:63], v58 offset:12032
	v_pk_mul_f32 v[102:103], v[24:25], v[56:57] op_sel_hi:[1,0]
	ds_read_b128 v[64:67], v58 offset:12048
	v_pk_mul_f32 v[110:111], v[24:25], v[56:57] op_sel:[0,1] op_sel_hi:[1,1]
	ds_read_b64 v[100:101], v59 offset:22784
	v_pk_mul_f32 v[104:105], v[26:27], v[56:57] op_sel_hi:[1,0]
	ds_read_b128 v[68:71], v58 offset:11776
	v_pk_mul_f32 v[112:113], v[26:27], v[56:57] op_sel:[0,1] op_sel_hi:[1,1]
	ds_read_b128 v[72:75], v58 offset:11792
	v_pk_mul_f32 v[106:107], v[28:29], v[56:57] op_sel_hi:[1,0]
	ds_read_b128 v[76:79], v58 offset:12288
	v_pk_mul_f32 v[114:115], v[28:29], v[56:57] op_sel:[0,1] op_sel_hi:[1,1]
	ds_read_b128 v[80:83], v58 offset:12304
	v_pk_mul_f32 v[108:109], v[30:31], v[56:57] op_sel_hi:[1,0]
	ds_read_b128 v[84:87], v58 offset:11520
	v_pk_mul_f32 v[116:117], v[30:31], v[56:57] op_sel:[0,1] op_sel_hi:[1,1]
	ds_read_b128 v[88:91], v58 offset:11536
	ds_read_b128 v[92:95], v58 offset:12544
	ds_read_b128 v[96:99], v58 offset:12560
	v_pk_fma_f32 v[102:103], v[32:33], v[122:123], v[102:103] op_sel_hi:[1,0,1]
	v_pk_fma_f32 v[110:111], v[32:33], v[122:123], v[110:111] op_sel:[0,1,0] op_sel_hi:[1,1,1]
	v_add_f32_dpp v133, v128, v128 row_ror:12 row_mask:0xf bank_mask:0x5 bound_ctrl:1
	v_pk_fma_f32 v[104:105], v[34:35], v[122:123], v[104:105] op_sel_hi:[1,0,1]
	v_pk_fma_f32 v[112:113], v[34:35], v[122:123], v[112:113] op_sel:[0,1,0] op_sel_hi:[1,1,1]
	v_add_f32_dpp v133, v129, v129 row_ror:4 row_mask:0xf bank_mask:0xa bound_ctrl:1
	v_pk_fma_f32 v[106:107], v[36:37], v[122:123], v[106:107] op_sel_hi:[1,0,1]
	v_pk_fma_f32 v[114:115], v[36:37], v[122:123], v[114:115] op_sel:[0,1,0] op_sel_hi:[1,1,1]
	v_add_f32_dpp v135, v130, v130 row_ror:12 row_mask:0xf bank_mask:0x5 bound_ctrl:1
	v_pk_fma_f32 v[108:109], v[38:39], v[122:123], v[108:109] op_sel_hi:[1,0,1]
	v_pk_fma_f32 v[116:117], v[38:39], v[122:123], v[116:117] op_sel:[0,1,0] op_sel_hi:[1,1,1]
	v_add_f32_dpp v135, v131, v131 row_ror:4 row_mask:0xf bank_mask:0xa bound_ctrl:1
	v_pk_fma_f32 v[0:1], v[0:1], v[40:41], v[102:103]
	v_pk_fma_f32 v[8:9], v[8:9], v[40:41], v[110:111]
	v_cndmask_b32_e64 v140, v132, v133, s[6:7]
	v_pk_fma_f32 v[2:3], v[2:3], v[42:43], v[104:105]
	v_pk_fma_f32 v[10:11], v[10:11], v[42:43], v[112:113]
	v_cndmask_b32_e64 v141, v133, v132, s[6:7]
	v_pk_fma_f32 v[4:5], v[4:5], v[44:45], v[106:107]
	v_pk_fma_f32 v[12:13], v[12:13], v[44:45], v[114:115]
	v_cndmask_b32_e64 v142, v134, v135, s[6:7]
	v_pk_fma_f32 v[6:7], v[6:7], v[46:47], v[108:109]
	v_pk_fma_f32 v[14:15], v[14:15], v[46:47], v[116:117]
	v_cndmask_b32_e64 v143, v135, v134, s[6:7]
	v_add_f32_dpp v137, v141, v140 quad_perm:[1,0,3,2] row_mask:0xf bank_mask:0xf bound_ctrl:1
	s_nop 0
	v_add_f32_dpp v139, v143, v142 quad_perm:[1,0,3,2] row_mask:0xf bank_mask:0xf bound_ctrl:1
	v_cndmask_b32_e64 v140, v136, v137, s[8:9]
	v_cndmask_b32_e64 v141, v137, v136, s[8:9]
	v_cndmask_b32_e64 v142, v138, v139, s[8:9]
	v_cndmask_b32_e64 v143, v139, v138, s[8:9]
	v_add_f32_dpp v144, v141, v140 quad_perm:[2,3,0,1] row_mask:0xf bank_mask:0xf bound_ctrl:1
	s_nop 0
	v_add_f32_dpp v145, v143, v142 quad_perm:[2,3,0,1] row_mask:0xf bank_mask:0xf bound_ctrl:1
	s_waitcnt lgkmcnt(9)
; DN void rw_scan_item(const Params& p, int l, int item, bool need_ctx, int mode) {
;     ...
;           for (int s8 = 0; s8 < 8; ++s8) {
;             const int s = hb * 8 + s8;
;             const float* vs = vec + s * 320 + j16 * 4;
;             const f32x4v w0 = *(const f32x4v*)(vs);
;             const f32x4v d0 = *(const f32x4v*)(vs + 64);
;             const f32x4v a0 = *(const f32x4v*)(vs + 128);
;             const f32x4v b0 = *(const f32x4v*)(vs + 192);
;             const f32x4v q0 = *(const f32x4v*)(vs + 256);
;             float sa[4], vi[4];
; #pragma unroll
;             for (int k = 0; k < 4; ++k) {
;               vi[k] = vvv[s * 64 + rq + 16 * k];
;               f32x2 t = S[k][0] * a0.xy;
;               t = S[k][1] * a0.zw + t;
;               sa[k] = t.x + t.y;
;             }
; #pragma unroll
;             for (int k = 0; k < 4; ++k) sa[k] += dppf<0xB1>(sa[k]);
; #pragma unroll
;             for (int k = 0; k < 4; ++k) sa[k] += dppf<0x4E>(sa[k]);
; #pragma unroll
;             for (int k = 0; k < 4; ++k) sa[k] += dppf<0x141>(sa[k]);
; #pragma unroll
;             for (int k = 0; k < 4; ++k) sa[k] += dppf<0x140>(sa[k]);
; #pragma unroll
;             for (int k = 0; k < 4; ++k) {
;               const f32x2 s2 = (f32x2){sa[k], sa[k]}, v2 = (f32x2){vi[k], vi[k]};
;               S[k][0] = S[k][0] * w0.xy + (s2 * b0.xy + v2 * d0.xy);
;               S[k][1] = S[k][1] * w0.zw + (s2 * b0.zw + v2 * d0.zw);
;               f32x2 y2 = S[k][0] * q0.xy;
;               y2 = S[k][1] * q0.zw + y2;
;               yp[k][s8] = y2.x + y2.y;
;             }
;           }
	v_pk_mul_f32 v[118:119], v[0:1], v[60:61]
	v_pk_mul_f32 v[120:121], v[8:9], v[60:61]
	v_pk_mul_f32 v[124:125], v[0:1], v[48:49]
	v_pk_fma_f32 v[118:119], v[2:3], v[62:63], v[118:119]
	v_pk_fma_f32 v[120:121], v[10:11], v[62:63], v[120:121]
	v_pk_mul_f32 v[126:127], v[8:9], v[48:49]
	v_pk_fma_f32 v[118:119], v[4:5], v[64:65], v[118:119]
	v_pk_fma_f32 v[120:121], v[12:13], v[64:65], v[120:121]
	v_pk_fma_f32 v[124:125], v[2:3], v[50:51], v[124:125]
	v_pk_fma_f32 v[118:119], v[6:7], v[66:67], v[118:119]
	v_pk_fma_f32 v[120:121], v[14:15], v[66:67], v[120:121]
	v_pk_fma_f32 v[126:127], v[10:11], v[50:51], v[126:127]
	v_add_f32_e32 v122, v118, v119
	v_add_f32_e32 v123, v120, v121
	v_pk_fma_f32 v[124:125], v[4:5], v[52:53], v[124:125]
	v_pk_fma_f32 v[126:127], v[12:13], v[52:53], v[126:127]
	v_add_f32_dpp v122, v122, v122 quad_perm:[1,0,3,2] row_mask:0xf bank_mask:0xf bound_ctrl:1
	v_add_f32_dpp v123, v123, v123 quad_perm:[1,0,3,2] row_mask:0xf bank_mask:0xf bound_ctrl:1
	v_pk_fma_f32 v[124:125], v[6:7], v[54:55], v[124:125]
	v_pk_fma_f32 v[126:127], v[14:15], v[54:55], v[126:127]
	v_add_f32_dpp v122, v122, v122 quad_perm:[2,3,0,1] row_mask:0xf bank_mask:0xf bound_ctrl:1
	v_add_f32_dpp v123, v123, v123 quad_perm:[2,3,0,1] row_mask:0xf bank_mask:0xf bound_ctrl:1
	v_add_f32_e32 v128, v124, v125
	v_add_f32_e32 v130, v126, v127
	v_add_f32_dpp v122, v122, v122 row_half_mirror row_mask:0xf bank_mask:0xf bound_ctrl:1
	v_add_f32_dpp v123, v123, v123 row_half_mirror row_mask:0xf bank_mask:0xf bound_ctrl:1
	s_waitcnt lgkmcnt(0)
	ds_read_b128 v[16:19], v58 offset:13312
	v_pk_mul_f32 v[102:103], v[68:69], v[100:101] op_sel_hi:[1,0]
	ds_read_b128 v[20:23], v58 offset:13328
	v_pk_mul_f32 v[110:111], v[68:69], v[100:101] op_sel:[0,1] op_sel_hi:[1,1]
	ds_read_b64 v[56:57], v59 offset:23040
	v_pk_mul_f32 v[104:105], v[70:71], v[100:101] op_sel_hi:[1,0]
	ds_read_b128 v[24:27], v58 offset:13056
	v_pk_mul_f32 v[112:113], v[70:71], v[100:101] op_sel:[0,1] op_sel_hi:[1,1]
	ds_read_b128 v[28:31], v58 offset:13072
	v_pk_mul_f32 v[106:107], v[72:73], v[100:101] op_sel_hi:[1,0]
	ds_read_b128 v[32:35], v58 offset:13568
	v_pk_mul_f32 v[114:115], v[72:73], v[100:101] op_sel:[0,1] op_sel_hi:[1,1]
	ds_read_b128 v[36:39], v58 offset:13584
	v_pk_mul_f32 v[108:109], v[74:75], v[100:101] op_sel_hi:[1,0]
	ds_read_b128 v[40:43], v58 offset:12800
	v_pk_mul_f32 v[116:117], v[74:75], v[100:101] op_sel:[0,1] op_sel_hi:[1,1]
	ds_read_b128 v[44:47], v58 offset:12816
	ds_read_b128 v[48:51], v58 offset:13824
	ds_read_b128 v[52:55], v58 offset:13840
	v_pk_fma_f32 v[102:103], v[76:77], v[122:123], v[102:103] op_sel_hi:[1,0,1]
	v_pk_fma_f32 v[110:111], v[76:77], v[122:123], v[110:111] op_sel:[0,1,0] op_sel_hi:[1,1,1]
	v_pk_fma_f32 v[104:105], v[78:79], v[122:123], v[104:105] op_sel_hi:[1,0,1]
	v_pk_fma_f32 v[112:113], v[78:79], v[122:123], v[112:113] op_sel:[0,1,0] op_sel_hi:[1,1,1]
	v_pk_fma_f32 v[106:107], v[80:81], v[122:123], v[106:107] op_sel_hi:[1,0,1]
	v_pk_fma_f32 v[114:115], v[80:81], v[122:123], v[114:115] op_sel:[0,1,0] op_sel_hi:[1,1,1]
	v_pk_fma_f32 v[108:109], v[82:83], v[122:123], v[108:109] op_sel_hi:[1,0,1]
	v_pk_fma_f32 v[116:117], v[82:83], v[122:123], v[116:117] op_sel:[0,1,0] op_sel_hi:[1,1,1]
	v_pk_fma_f32 v[0:1], v[0:1], v[84:85], v[102:103]
	v_pk_fma_f32 v[8:9], v[8:9], v[84:85], v[110:111]
	v_pk_fma_f32 v[2:3], v[2:3], v[86:87], v[104:105]
	v_pk_fma_f32 v[10:11], v[10:11], v[86:87], v[112:113]
	v_pk_fma_f32 v[4:5], v[4:5], v[88:89], v[106:107]
	v_pk_fma_f32 v[12:13], v[12:13], v[88:89], v[114:115]
	v_pk_fma_f32 v[6:7], v[6:7], v[90:91], v[108:109]
	v_pk_fma_f32 v[14:15], v[14:15], v[90:91], v[116:117]
	s_waitcnt lgkmcnt(9)
	v_pk_mul_f32 v[118:119], v[0:1], v[16:17]
	v_pk_mul_f32 v[120:121], v[8:9], v[16:17]
	v_pk_mul_f32 v[124:125], v[0:1], v[92:93]
	v_pk_fma_f32 v[118:119], v[2:3], v[18:19], v[118:119]
	v_pk_fma_f32 v[120:121], v[10:11], v[18:19], v[120:121]
	v_pk_mul_f32 v[126:127], v[8:9], v[92:93]
	v_pk_fma_f32 v[118:119], v[4:5], v[20:21], v[118:119]
	v_pk_fma_f32 v[120:121], v[12:13], v[20:21], v[120:121]
	v_pk_fma_f32 v[124:125], v[2:3], v[94:95], v[124:125]
	v_pk_fma_f32 v[118:119], v[6:7], v[22:23], v[118:119]
	v_pk_fma_f32 v[120:121], v[14:15], v[22:23], v[120:121]
	v_pk_fma_f32 v[126:127], v[10:11], v[94:95], v[126:127]
	v_add_f32_e32 v122, v118, v119
	v_add_f32_e32 v123, v120, v121
	v_pk_fma_f32 v[124:125], v[4:5], v[96:97], v[124:125]
	v_pk_fma_f32 v[126:127], v[12:13], v[96:97], v[126:127]
	v_add_f32_dpp v122, v122, v122 quad_perm:[1,0,3,2] row_mask:0xf bank_mask:0xf bound_ctrl:1
	v_add_f32_dpp v123, v123, v123 quad_perm:[1,0,3,2] row_mask:0xf bank_mask:0xf bound_ctrl:1
	v_pk_fma_f32 v[124:125], v[6:7], v[98:99], v[124:125]
	v_pk_fma_f32 v[126:127], v[14:15], v[98:99], v[126:127]
	v_add_f32_dpp v122, v122, v122 quad_perm:[2,3,0,1] row_mask:0xf bank_mask:0xf bound_ctrl:1
	v_add_f32_dpp v123, v123, v123 quad_perm:[2,3,0,1] row_mask:0xf bank_mask:0xf bound_ctrl:1
	v_add_f32_e32 v129, v124, v125
	v_add_f32_e32 v131, v126, v127
	v_add_f32_dpp v122, v122, v122 row_half_mirror row_mask:0xf bank_mask:0xf bound_ctrl:1
	v_add_f32_dpp v123, v123, v123 row_half_mirror row_mask:0xf bank_mask:0xf bound_ctrl:1
	s_waitcnt lgkmcnt(0)
; DN void rw_scan_item(const Params& p, int l, int item, bool need_ctx, int mode) {
;     ...
;           for (int s8 = 0; s8 < 8; ++s8) {
;             const int s = hb * 8 + s8;
;             const float* vs = vec + s * 320 + j16 * 4;
;             const f32x4v w0 = *(const f32x4v*)(vs);
;             const f32x4v d0 = *(const f32x4v*)(vs + 64);
;             const f32x4v a0 = *(const f32x4v*)(vs + 128);
;             const f32x4v b0 = *(const f32x4v*)(vs + 192);
;             const f32x4v q0 = *(const f32x4v*)(vs + 256);
;             float sa[4], vi[4];
; #pragma unroll
;             for (int k = 0; k < 4; ++k) {
;               vi[k] = vvv[s * 64 + rq + 16 * k];
;               f32x2 t = S[k][0] * a0.xy;
;               t = S[k][1] * a0.zw + t;
;               sa[k] = t.x + t.y;
;             }
; #pragma unroll
;             for (int k = 0; k < 4; ++k) sa[k] += dppf<0xB1>(sa[k]);
; #pragma unroll
;             for (int k = 0; k < 4; ++k) sa[k] += dppf<0x4E>(sa[k]);
; #pragma unroll
;             for (int k = 0; k < 4; ++k) sa[k] += dppf<0x141>(sa[k]);
; #pragma unroll
;             for (int k = 0; k < 4; ++k) sa[k] += dppf<0x140>(sa[k]);
; #pragma unroll
;             for (int k = 0; k < 4; ++k) {
;               const f32x2 s2 = (f32x2){sa[k], sa[k]}, v2 = (f32x2){vi[k], vi[k]};
;               S[k][0] = S[k][0] * w0.xy + (s2 * b0.xy + v2 * d0.xy);
;               S[k][1] = S[k][1] * w0.zw + (s2 * b0.zw + v2 * d0.zw);
;               f32x2 y2 = S[k][0] * q0.xy;
;               y2 = S[k][1] * q0.zw + y2;
;               yp[k][s8] = y2.x + y2.y;
;             }
;           }
	ds_read_b128 v[60:63], v58 offset:14592
	v_pk_mul_f32 v[102:103], v[24:25], v[56:57] op_sel_hi:[1,0]
	ds_read_b128 v[64:67], v58 offset:14608
	v_pk_mul_f32 v[110:111], v[24:25], v[56:57] op_sel:[0,1] op_sel_hi:[1,1]
	ds_read_b64 v[100:101], v59 offset:23296
	v_pk_mul_f32 v[104:105], v[26:27], v[56:57] op_sel_hi:[1,0]
	ds_read_b128 v[68:71], v58 offset:14336
	v_pk_mul_f32 v[112:113], v[26:27], v[56:57] op_sel:[0,1] op_sel_hi:[1,1]
	ds_read_b128 v[72:75], v58 offset:14352
	v_pk_mul_f32 v[106:107], v[28:29], v[56:57] op_sel_hi:[1,0]
	ds_read_b128 v[76:79], v58 offset:14848
	v_pk_mul_f32 v[114:115], v[28:29], v[56:57] op_sel:[0,1] op_sel_hi:[1,1]
	ds_read_b128 v[80:83], v58 offset:14864
	v_pk_mul_f32 v[108:109], v[30:31], v[56:57] op_sel_hi:[1,0]
	ds_read_b128 v[84:87], v58 offset:14080
	v_pk_mul_f32 v[116:117], v[30:31], v[56:57] op_sel:[0,1] op_sel_hi:[1,1]
	ds_read_b128 v[88:91], v58 offset:14096
	ds_read_b128 v[92:95], v58 offset:15104
	ds_read_b128 v[96:99], v58 offset:15120
	v_pk_fma_f32 v[102:103], v[32:33], v[122:123], v[102:103] op_sel_hi:[1,0,1]
	v_pk_fma_f32 v[110:111], v[32:33], v[122:123], v[110:111] op_sel:[0,1,0] op_sel_hi:[1,1,1]
	v_add_f32_dpp v132, v128, v128 row_ror:12 row_mask:0xf bank_mask:0x5 bound_ctrl:1
	v_pk_fma_f32 v[104:105], v[34:35], v[122:123], v[104:105] op_sel_hi:[1,0,1]
	v_pk_fma_f32 v[112:113], v[34:35], v[122:123], v[112:113] op_sel:[0,1,0] op_sel_hi:[1,1,1]
	v_add_f32_dpp v132, v129, v129 row_ror:4 row_mask:0xf bank_mask:0xa bound_ctrl:1
	v_pk_fma_f32 v[106:107], v[36:37], v[122:123], v[106:107] op_sel_hi:[1,0,1]
	v_pk_fma_f32 v[114:115], v[36:37], v[122:123], v[114:115] op_sel:[0,1,0] op_sel_hi:[1,1,1]
	v_add_f32_dpp v134, v130, v130 row_ror:12 row_mask:0xf bank_mask:0x5 bound_ctrl:1
	v_pk_fma_f32 v[108:109], v[38:39], v[122:123], v[108:109] op_sel_hi:[1,0,1]
	v_pk_fma_f32 v[116:117], v[38:39], v[122:123], v[116:117] op_sel:[0,1,0] op_sel_hi:[1,1,1]
	v_add_f32_dpp v134, v131, v131 row_ror:4 row_mask:0xf bank_mask:0xa bound_ctrl:1
	v_pk_fma_f32 v[0:1], v[0:1], v[40:41], v[102:103]
	v_pk_fma_f32 v[8:9], v[8:9], v[40:41], v[110:111]
	v_pk_fma_f32 v[2:3], v[2:3], v[42:43], v[104:105]
	v_pk_fma_f32 v[10:11], v[10:11], v[42:43], v[112:113]
	v_pk_fma_f32 v[4:5], v[4:5], v[44:45], v[106:107]
	v_pk_fma_f32 v[12:13], v[12:13], v[44:45], v[114:115]
	v_pk_fma_f32 v[6:7], v[6:7], v[46:47], v[108:109]
	v_pk_fma_f32 v[14:15], v[14:15], v[46:47], v[116:117]
	s_waitcnt lgkmcnt(9)
	v_pk_mul_f32 v[118:119], v[0:1], v[60:61]
	v_pk_mul_f32 v[120:121], v[8:9], v[60:61]
	v_pk_mul_f32 v[124:125], v[0:1], v[48:49]
	v_pk_fma_f32 v[118:119], v[2:3], v[62:63], v[118:119]
	v_pk_fma_f32 v[120:121], v[10:11], v[62:63], v[120:121]
	v_pk_mul_f32 v[126:127], v[8:9], v[48:49]
	v_pk_fma_f32 v[118:119], v[4:5], v[64:65], v[118:119]
	v_pk_fma_f32 v[120:121], v[12:13], v[64:65], v[120:121]
	v_pk_fma_f32 v[124:125], v[2:3], v[50:51], v[124:125]
	v_pk_fma_f32 v[118:119], v[6:7], v[66:67], v[118:119]
	v_pk_fma_f32 v[120:121], v[14:15], v[66:67], v[120:121]
	v_pk_fma_f32 v[126:127], v[10:11], v[50:51], v[126:127]
	v_add_f32_e32 v122, v118, v119
	v_add_f32_e32 v123, v120, v121
	v_pk_fma_f32 v[124:125], v[4:5], v[52:53], v[124:125]
	v_pk_fma_f32 v[126:127], v[12:13], v[52:53], v[126:127]
	v_add_f32_dpp v122, v122, v122 quad_perm:[1,0,3,2] row_mask:0xf bank_mask:0xf bound_ctrl:1
	v_add_f32_dpp v123, v123, v123 quad_perm:[1,0,3,2] row_mask:0xf bank_mask:0xf bound_ctrl:1
	v_pk_fma_f32 v[124:125], v[6:7], v[54:55], v[124:125]
	v_pk_fma_f32 v[126:127], v[14:15], v[54:55], v[126:127]
	v_add_f32_dpp v122, v122, v122 quad_perm:[2,3,0,1] row_mask:0xf bank_mask:0xf bound_ctrl:1
	v_add_f32_dpp v123, v123, v123 quad_perm:[2,3,0,1] row_mask:0xf bank_mask:0xf bound_ctrl:1
	v_add_f32_e32 v128, v124, v125
	v_add_f32_e32 v130, v126, v127
	v_add_f32_dpp v122, v122, v122 row_half_mirror row_mask:0xf bank_mask:0xf bound_ctrl:1
	v_add_f32_dpp v123, v123, v123 row_half_mirror row_mask:0xf bank_mask:0xf bound_ctrl:1
	s_waitcnt lgkmcnt(0)
	ds_read_b128 v[16:19], v58 offset:15872
	v_pk_mul_f32 v[102:103], v[68:69], v[100:101] op_sel_hi:[1,0]
	ds_read_b128 v[20:23], v58 offset:15888
	v_pk_mul_f32 v[110:111], v[68:69], v[100:101] op_sel:[0,1] op_sel_hi:[1,1]
	ds_read_b64 v[56:57], v59 offset:23552
	v_pk_mul_f32 v[104:105], v[70:71], v[100:101] op_sel_hi:[1,0]
	ds_read_b128 v[24:27], v58 offset:15616
	v_pk_mul_f32 v[112:113], v[70:71], v[100:101] op_sel:[0,1] op_sel_hi:[1,1]
	ds_read_b128 v[28:31], v58 offset:15632
	v_pk_mul_f32 v[106:107], v[72:73], v[100:101] op_sel_hi:[1,0]
	ds_read_b128 v[32:35], v58 offset:16128
	v_pk_mul_f32 v[114:115], v[72:73], v[100:101] op_sel:[0,1] op_sel_hi:[1,1]
	ds_read_b128 v[36:39], v58 offset:16144
	v_pk_mul_f32 v[108:109], v[74:75], v[100:101] op_sel_hi:[1,0]
	ds_read_b128 v[40:43], v58 offset:15360
	v_pk_mul_f32 v[116:117], v[74:75], v[100:101] op_sel:[0,1] op_sel_hi:[1,1]
	ds_read_b128 v[44:47], v58 offset:15376
	ds_read_b128 v[48:51], v58 offset:16384
	ds_read_b128 v[52:55], v58 offset:16400
	v_pk_fma_f32 v[102:103], v[76:77], v[122:123], v[102:103] op_sel_hi:[1,0,1]
	v_pk_fma_f32 v[110:111], v[76:77], v[122:123], v[110:111] op_sel:[0,1,0] op_sel_hi:[1,1,1]
	v_pk_fma_f32 v[104:105], v[78:79], v[122:123], v[104:105] op_sel_hi:[1,0,1]
	v_pk_fma_f32 v[112:113], v[78:79], v[122:123], v[112:113] op_sel:[0,1,0] op_sel_hi:[1,1,1]
	v_pk_fma_f32 v[106:107], v[80:81], v[122:123], v[106:107] op_sel_hi:[1,0,1]
	v_pk_fma_f32 v[114:115], v[80:81], v[122:123], v[114:115] op_sel:[0,1,0] op_sel_hi:[1,1,1]
	v_pk_fma_f32 v[108:109], v[82:83], v[122:123], v[108:109] op_sel_hi:[1,0,1]
	v_pk_fma_f32 v[116:117], v[82:83], v[122:123], v[116:117] op_sel:[0,1,0] op_sel_hi:[1,1,1]
	v_pk_fma_f32 v[0:1], v[0:1], v[84:85], v[102:103]
	v_pk_fma_f32 v[8:9], v[8:9], v[84:85], v[110:111]
	v_pk_fma_f32 v[2:3], v[2:3], v[86:87], v[104:105]
	v_pk_fma_f32 v[10:11], v[10:11], v[86:87], v[112:113]
	v_pk_fma_f32 v[4:5], v[4:5], v[88:89], v[106:107]
	v_pk_fma_f32 v[12:13], v[12:13], v[88:89], v[114:115]
	v_pk_fma_f32 v[6:7], v[6:7], v[90:91], v[108:109]
	v_pk_fma_f32 v[14:15], v[14:15], v[90:91], v[116:117]
	s_waitcnt lgkmcnt(9)
; DN void rw_scan_item(const Params& p, int l, int item, bool need_ctx, int mode) {
;     ...
;           for (int s8 = 0; s8 < 8; ++s8) {
;             const int s = hb * 8 + s8;
;             const float* vs = vec + s * 320 + j16 * 4;
;             const f32x4v w0 = *(const f32x4v*)(vs);
;             const f32x4v d0 = *(const f32x4v*)(vs + 64);
;             const f32x4v a0 = *(const f32x4v*)(vs + 128);
;             const f32x4v b0 = *(const f32x4v*)(vs + 192);
;             const f32x4v q0 = *(const f32x4v*)(vs + 256);
;             float sa[4], vi[4];
; #pragma unroll
;             for (int k = 0; k < 4; ++k) {
;               vi[k] = vvv[s * 64 + rq + 16 * k];
;               f32x2 t = S[k][0] * a0.xy;
;               t = S[k][1] * a0.zw + t;
;               sa[k] = t.x + t.y;
;             }
; #pragma unroll
;             for (int k = 0; k < 4; ++k) sa[k] += dppf<0xB1>(sa[k]);
; #pragma unroll
;             for (int k = 0; k < 4; ++k) sa[k] += dppf<0x4E>(sa[k]);
; #pragma unroll
;             for (int k = 0; k < 4; ++k) sa[k] += dppf<0x141>(sa[k]);
; #pragma unroll
;             for (int k = 0; k < 4; ++k) sa[k] += dppf<0x140>(sa[k]);
; #pragma unroll
;             for (int k = 0; k < 4; ++k) {
;               const f32x2 s2 = (f32x2){sa[k], sa[k]}, v2 = (f32x2){vi[k], vi[k]};
;               S[k][0] = S[k][0] * w0.xy + (s2 * b0.xy + v2 * d0.xy);
;               S[k][1] = S[k][1] * w0.zw + (s2 * b0.zw + v2 * d0.zw);
;               f32x2 y2 = S[k][0] * q0.xy;
;               y2 = S[k][1] * q0.zw + y2;
;               yp[k][s8] = y2.x + y2.y;
;             }
;           }
	v_pk_mul_f32 v[118:119], v[0:1], v[16:17]
	v_pk_mul_f32 v[120:121], v[8:9], v[16:17]
	v_pk_mul_f32 v[124:125], v[0:1], v[92:93]
	v_pk_fma_f32 v[118:119], v[2:3], v[18:19], v[118:119]
	v_pk_fma_f32 v[120:121], v[10:11], v[18:19], v[120:121]
	v_pk_mul_f32 v[126:127], v[8:9], v[92:93]
	v_pk_fma_f32 v[118:119], v[4:5], v[20:21], v[118:119]
	v_pk_fma_f32 v[120:121], v[12:13], v[20:21], v[120:121]
	v_pk_fma_f32 v[124:125], v[2:3], v[94:95], v[124:125]
	v_pk_fma_f32 v[118:119], v[6:7], v[22:23], v[118:119]
	v_pk_fma_f32 v[120:121], v[14:15], v[22:23], v[120:121]
	v_pk_fma_f32 v[126:127], v[10:11], v[94:95], v[126:127]
	v_add_f32_e32 v122, v118, v119
	v_add_f32_e32 v123, v120, v121
	v_pk_fma_f32 v[124:125], v[4:5], v[96:97], v[124:125]
	v_pk_fma_f32 v[126:127], v[12:13], v[96:97], v[126:127]
	v_add_f32_dpp v122, v122, v122 quad_perm:[1,0,3,2] row_mask:0xf bank_mask:0xf bound_ctrl:1
	v_add_f32_dpp v123, v123, v123 quad_perm:[1,0,3,2] row_mask:0xf bank_mask:0xf bound_ctrl:1
	v_pk_fma_f32 v[124:125], v[6:7], v[98:99], v[124:125]
	v_pk_fma_f32 v[126:127], v[14:15], v[98:99], v[126:127]
	v_add_f32_dpp v122, v122, v122 quad_perm:[2,3,0,1] row_mask:0xf bank_mask:0xf bound_ctrl:1
	v_add_f32_dpp v123, v123, v123 quad_perm:[2,3,0,1] row_mask:0xf bank_mask:0xf bound_ctrl:1
	v_add_f32_e32 v129, v124, v125
	v_add_f32_e32 v131, v126, v127
	v_add_f32_dpp v122, v122, v122 row_half_mirror row_mask:0xf bank_mask:0xf bound_ctrl:1
	v_add_f32_dpp v123, v123, v123 row_half_mirror row_mask:0xf bank_mask:0xf bound_ctrl:1
	s_waitcnt lgkmcnt(0)
	ds_read_b128 v[60:63], v58 offset:17152
	v_pk_mul_f32 v[102:103], v[24:25], v[56:57] op_sel_hi:[1,0]
	ds_read_b128 v[64:67], v58 offset:17168
	v_pk_mul_f32 v[110:111], v[24:25], v[56:57] op_sel:[0,1] op_sel_hi:[1,1]
	ds_read_b64 v[100:101], v59 offset:23808
	v_pk_mul_f32 v[104:105], v[26:27], v[56:57] op_sel_hi:[1,0]
	ds_read_b128 v[68:71], v58 offset:16896
	v_pk_mul_f32 v[112:113], v[26:27], v[56:57] op_sel:[0,1] op_sel_hi:[1,1]
	ds_read_b128 v[72:75], v58 offset:16912
	v_pk_mul_f32 v[106:107], v[28:29], v[56:57] op_sel_hi:[1,0]
	ds_read_b128 v[76:79], v58 offset:17408
	v_pk_mul_f32 v[114:115], v[28:29], v[56:57] op_sel:[0,1] op_sel_hi:[1,1]
	ds_read_b128 v[80:83], v58 offset:17424
	v_pk_mul_f32 v[108:109], v[30:31], v[56:57] op_sel_hi:[1,0]
	ds_read_b128 v[84:87], v58 offset:16640
	v_pk_mul_f32 v[116:117], v[30:31], v[56:57] op_sel:[0,1] op_sel_hi:[1,1]
	ds_read_b128 v[88:91], v58 offset:16656
	ds_read_b128 v[92:95], v58 offset:17664
	ds_read_b128 v[96:99], v58 offset:17680
	v_pk_fma_f32 v[102:103], v[32:33], v[122:123], v[102:103] op_sel_hi:[1,0,1]
	v_pk_fma_f32 v[110:111], v[32:33], v[122:123], v[110:111] op_sel:[0,1,0] op_sel_hi:[1,1,1]
	v_add_f32_dpp v133, v128, v128 row_ror:12 row_mask:0xf bank_mask:0x5 bound_ctrl:1
	v_pk_fma_f32 v[104:105], v[34:35], v[122:123], v[104:105] op_sel_hi:[1,0,1]
	v_pk_fma_f32 v[112:113], v[34:35], v[122:123], v[112:113] op_sel:[0,1,0] op_sel_hi:[1,1,1]
	v_add_f32_dpp v133, v129, v129 row_ror:4 row_mask:0xf bank_mask:0xa bound_ctrl:1
	v_pk_fma_f32 v[106:107], v[36:37], v[122:123], v[106:107] op_sel_hi:[1,0,1]
	v_pk_fma_f32 v[114:115], v[36:37], v[122:123], v[114:115] op_sel:[0,1,0] op_sel_hi:[1,1,1]
	v_add_f32_dpp v135, v130, v130 row_ror:12 row_mask:0xf bank_mask:0x5 bound_ctrl:1
	v_pk_fma_f32 v[108:109], v[38:39], v[122:123], v[108:109] op_sel_hi:[1,0,1]
	v_pk_fma_f32 v[116:117], v[38:39], v[122:123], v[116:117] op_sel:[0,1,0] op_sel_hi:[1,1,1]
	v_add_f32_dpp v135, v131, v131 row_ror:4 row_mask:0xf bank_mask:0xa bound_ctrl:1
	v_pk_fma_f32 v[0:1], v[0:1], v[40:41], v[102:103]
	v_pk_fma_f32 v[8:9], v[8:9], v[40:41], v[110:111]
	v_cndmask_b32_e64 v140, v132, v133, s[6:7]
	v_pk_fma_f32 v[2:3], v[2:3], v[42:43], v[104:105]
	v_pk_fma_f32 v[10:11], v[10:11], v[42:43], v[112:113]
	v_cndmask_b32_e64 v141, v133, v132, s[6:7]
	v_pk_fma_f32 v[4:5], v[4:5], v[44:45], v[106:107]
	v_pk_fma_f32 v[12:13], v[12:13], v[44:45], v[114:115]
	v_cndmask_b32_e64 v142, v134, v135, s[6:7]
	v_pk_fma_f32 v[6:7], v[6:7], v[46:47], v[108:109]
	v_pk_fma_f32 v[14:15], v[14:15], v[46:47], v[116:117]
	v_cndmask_b32_e64 v143, v135, v134, s[6:7]
	v_add_f32_dpp v136, v141, v140 quad_perm:[1,0,3,2] row_mask:0xf bank_mask:0xf bound_ctrl:1
	s_nop 0
	v_add_f32_dpp v138, v143, v142 quad_perm:[1,0,3,2] row_mask:0xf bank_mask:0xf bound_ctrl:1
	s_waitcnt lgkmcnt(9)
	v_pk_mul_f32 v[118:119], v[0:1], v[60:61]
	v_pk_mul_f32 v[120:121], v[8:9], v[60:61]
	v_pk_mul_f32 v[124:125], v[0:1], v[48:49]
	v_pk_fma_f32 v[118:119], v[2:3], v[62:63], v[118:119]
	v_pk_fma_f32 v[120:121], v[10:11], v[62:63], v[120:121]
	v_pk_mul_f32 v[126:127], v[8:9], v[48:49]
	v_pk_fma_f32 v[118:119], v[4:5], v[64:65], v[118:119]
	v_pk_fma_f32 v[120:121], v[12:13], v[64:65], v[120:121]
	v_pk_fma_f32 v[124:125], v[2:3], v[50:51], v[124:125]
	v_pk_fma_f32 v[118:119], v[6:7], v[66:67], v[118:119]
	v_pk_fma_f32 v[120:121], v[14:15], v[66:67], v[120:121]
	v_pk_fma_f32 v[126:127], v[10:11], v[50:51], v[126:127]
	v_add_f32_e32 v122, v118, v119
	v_add_f32_e32 v123, v120, v121
	v_pk_fma_f32 v[124:125], v[4:5], v[52:53], v[124:125]
	v_pk_fma_f32 v[126:127], v[12:13], v[52:53], v[126:127]
	v_add_f32_dpp v122, v122, v122 quad_perm:[1,0,3,2] row_mask:0xf bank_mask:0xf bound_ctrl:1
	v_add_f32_dpp v123, v123, v123 quad_perm:[1,0,3,2] row_mask:0xf bank_mask:0xf bound_ctrl:1
	v_pk_fma_f32 v[124:125], v[6:7], v[54:55], v[124:125]
	v_pk_fma_f32 v[126:127], v[14:15], v[54:55], v[126:127]
	v_add_f32_dpp v122, v122, v122 quad_perm:[2,3,0,1] row_mask:0xf bank_mask:0xf bound_ctrl:1
	v_add_f32_dpp v123, v123, v123 quad_perm:[2,3,0,1] row_mask:0xf bank_mask:0xf bound_ctrl:1
	v_add_f32_e32 v128, v124, v125
	v_add_f32_e32 v130, v126, v127
	v_add_f32_dpp v122, v122, v122 row_half_mirror row_mask:0xf bank_mask:0xf bound_ctrl:1
	v_add_f32_dpp v123, v123, v123 row_half_mirror row_mask:0xf bank_mask:0xf bound_ctrl:1
	s_waitcnt lgkmcnt(0)
; DN void rw_scan_item(const Params& p, int l, int item, bool need_ctx, int mode) {
;     ...
;           for (int s8 = 0; s8 < 8; ++s8) {
;             const int s = hb * 8 + s8;
;             const float* vs = vec + s * 320 + j16 * 4;
;             const f32x4v w0 = *(const f32x4v*)(vs);
;             const f32x4v d0 = *(const f32x4v*)(vs + 64);
;             const f32x4v a0 = *(const f32x4v*)(vs + 128);
;             const f32x4v b0 = *(const f32x4v*)(vs + 192);
;             const f32x4v q0 = *(const f32x4v*)(vs + 256);
;             float sa[4], vi[4];
; #pragma unroll
;             for (int k = 0; k < 4; ++k) {
;               vi[k] = vvv[s * 64 + rq + 16 * k];
;               f32x2 t = S[k][0] * a0.xy;
;               t = S[k][1] * a0.zw + t;
;               sa[k] = t.x + t.y;
;             }
; #pragma unroll
;             for (int k = 0; k < 4; ++k) sa[k] += dppf<0xB1>(sa[k]);
; #pragma unroll
;             for (int k = 0; k < 4; ++k) sa[k] += dppf<0x4E>(sa[k]);
; #pragma unroll
;             for (int k = 0; k < 4; ++k) sa[k] += dppf<0x141>(sa[k]);
; #pragma unroll
;             for (int k = 0; k < 4; ++k) sa[k] += dppf<0x140>(sa[k]);
; #pragma unroll
;             for (int k = 0; k < 4; ++k) {
;               const f32x2 s2 = (f32x2){sa[k], sa[k]}, v2 = (f32x2){vi[k], vi[k]};
;               S[k][0] = S[k][0] * w0.xy + (s2 * b0.xy + v2 * d0.xy);
;               S[k][1] = S[k][1] * w0.zw + (s2 * b0.zw + v2 * d0.zw);
;               f32x2 y2 = S[k][0] * q0.xy;
;               y2 = S[k][1] * q0.zw + y2;
;               yp[k][s8] = y2.x + y2.y;
;             }
;           }
	ds_read_b128 v[16:19], v58 offset:18432
	v_pk_mul_f32 v[102:103], v[68:69], v[100:101] op_sel_hi:[1,0]
	ds_read_b128 v[20:23], v58 offset:18448
	v_pk_mul_f32 v[110:111], v[68:69], v[100:101] op_sel:[0,1] op_sel_hi:[1,1]
	ds_read_b64 v[56:57], v59 offset:24064
	v_pk_mul_f32 v[104:105], v[70:71], v[100:101] op_sel_hi:[1,0]
	ds_read_b128 v[24:27], v58 offset:18176
	v_pk_mul_f32 v[112:113], v[70:71], v[100:101] op_sel:[0,1] op_sel_hi:[1,1]
	ds_read_b128 v[28:31], v58 offset:18192
	v_pk_mul_f32 v[106:107], v[72:73], v[100:101] op_sel_hi:[1,0]
	ds_read_b128 v[32:35], v58 offset:18688
	v_pk_mul_f32 v[114:115], v[72:73], v[100:101] op_sel:[0,1] op_sel_hi:[1,1]
	ds_read_b128 v[36:39], v58 offset:18704
	v_pk_mul_f32 v[108:109], v[74:75], v[100:101] op_sel_hi:[1,0]
	ds_read_b128 v[40:43], v58 offset:17920
	v_pk_mul_f32 v[116:117], v[74:75], v[100:101] op_sel:[0,1] op_sel_hi:[1,1]
	ds_read_b128 v[44:47], v58 offset:17936
	ds_read_b128 v[48:51], v58 offset:18944
	ds_read_b128 v[52:55], v58 offset:18960
	v_pk_fma_f32 v[102:103], v[76:77], v[122:123], v[102:103] op_sel_hi:[1,0,1]
	v_pk_fma_f32 v[110:111], v[76:77], v[122:123], v[110:111] op_sel:[0,1,0] op_sel_hi:[1,1,1]
	v_pk_fma_f32 v[104:105], v[78:79], v[122:123], v[104:105] op_sel_hi:[1,0,1]
	v_pk_fma_f32 v[112:113], v[78:79], v[122:123], v[112:113] op_sel:[0,1,0] op_sel_hi:[1,1,1]
	v_pk_fma_f32 v[106:107], v[80:81], v[122:123], v[106:107] op_sel_hi:[1,0,1]
	v_pk_fma_f32 v[114:115], v[80:81], v[122:123], v[114:115] op_sel:[0,1,0] op_sel_hi:[1,1,1]
	v_pk_fma_f32 v[108:109], v[82:83], v[122:123], v[108:109] op_sel_hi:[1,0,1]
	v_pk_fma_f32 v[116:117], v[82:83], v[122:123], v[116:117] op_sel:[0,1,0] op_sel_hi:[1,1,1]
	v_pk_fma_f32 v[0:1], v[0:1], v[84:85], v[102:103]
	v_pk_fma_f32 v[8:9], v[8:9], v[84:85], v[110:111]
	v_pk_fma_f32 v[2:3], v[2:3], v[86:87], v[104:105]
	v_pk_fma_f32 v[10:11], v[10:11], v[86:87], v[112:113]
	v_pk_fma_f32 v[4:5], v[4:5], v[88:89], v[106:107]
	v_pk_fma_f32 v[12:13], v[12:13], v[88:89], v[114:115]
	v_pk_fma_f32 v[6:7], v[6:7], v[90:91], v[108:109]
	v_pk_fma_f32 v[14:15], v[14:15], v[90:91], v[116:117]
	s_waitcnt lgkmcnt(9)
	v_pk_mul_f32 v[118:119], v[0:1], v[16:17]
	v_pk_mul_f32 v[120:121], v[8:9], v[16:17]
	v_pk_mul_f32 v[124:125], v[0:1], v[92:93]
	v_pk_fma_f32 v[118:119], v[2:3], v[18:19], v[118:119]
	v_pk_fma_f32 v[120:121], v[10:11], v[18:19], v[120:121]
	v_pk_mul_f32 v[126:127], v[8:9], v[92:93]
	v_pk_fma_f32 v[118:119], v[4:5], v[20:21], v[118:119]
	v_pk_fma_f32 v[120:121], v[12:13], v[20:21], v[120:121]
	v_pk_fma_f32 v[124:125], v[2:3], v[94:95], v[124:125]
	v_pk_fma_f32 v[118:119], v[6:7], v[22:23], v[118:119]
	v_pk_fma_f32 v[120:121], v[14:15], v[22:23], v[120:121]
	v_pk_fma_f32 v[126:127], v[10:11], v[94:95], v[126:127]
	v_add_f32_e32 v122, v118, v119
	v_add_f32_e32 v123, v120, v121
	v_pk_fma_f32 v[124:125], v[4:5], v[96:97], v[124:125]
	v_pk_fma_f32 v[126:127], v[12:13], v[96:97], v[126:127]
	v_add_f32_dpp v122, v122, v122 quad_perm:[1,0,3,2] row_mask:0xf bank_mask:0xf bound_ctrl:1
	v_add_f32_dpp v123, v123, v123 quad_perm:[1,0,3,2] row_mask:0xf bank_mask:0xf bound_ctrl:1
	v_pk_fma_f32 v[124:125], v[6:7], v[98:99], v[124:125]
	v_pk_fma_f32 v[126:127], v[14:15], v[98:99], v[126:127]
	v_add_f32_dpp v122, v122, v122 quad_perm:[2,3,0,1] row_mask:0xf bank_mask:0xf bound_ctrl:1
	v_add_f32_dpp v123, v123, v123 quad_perm:[2,3,0,1] row_mask:0xf bank_mask:0xf bound_ctrl:1
	v_add_f32_e32 v129, v124, v125
	v_add_f32_e32 v131, v126, v127
	v_add_f32_dpp v122, v122, v122 row_half_mirror row_mask:0xf bank_mask:0xf bound_ctrl:1
	v_add_f32_dpp v123, v123, v123 row_half_mirror row_mask:0xf bank_mask:0xf bound_ctrl:1
	s_waitcnt lgkmcnt(0)
	ds_read_b128 v[60:63], v58 offset:19712
	v_pk_mul_f32 v[102:103], v[24:25], v[56:57] op_sel_hi:[1,0]
	ds_read_b128 v[64:67], v58 offset:19728
	v_pk_mul_f32 v[110:111], v[24:25], v[56:57] op_sel:[0,1] op_sel_hi:[1,1]
	ds_read_b64 v[100:101], v59 offset:24320
	v_pk_mul_f32 v[104:105], v[26:27], v[56:57] op_sel_hi:[1,0]
	ds_read_b128 v[68:71], v58 offset:19456
	v_pk_mul_f32 v[112:113], v[26:27], v[56:57] op_sel:[0,1] op_sel_hi:[1,1]
	ds_read_b128 v[72:75], v58 offset:19472
	v_pk_mul_f32 v[106:107], v[28:29], v[56:57] op_sel_hi:[1,0]
	ds_read_b128 v[76:79], v58 offset:19968
	v_pk_mul_f32 v[114:115], v[28:29], v[56:57] op_sel:[0,1] op_sel_hi:[1,1]
	ds_read_b128 v[80:83], v58 offset:19984
	v_pk_mul_f32 v[108:109], v[30:31], v[56:57] op_sel_hi:[1,0]
	ds_read_b128 v[84:87], v58 offset:19200
	v_pk_mul_f32 v[116:117], v[30:31], v[56:57] op_sel:[0,1] op_sel_hi:[1,1]
	ds_read_b128 v[88:91], v58 offset:19216
	ds_read_b128 v[92:95], v58 offset:20224
	ds_read_b128 v[96:99], v58 offset:20240
	v_pk_fma_f32 v[102:103], v[32:33], v[122:123], v[102:103] op_sel_hi:[1,0,1]
	v_pk_fma_f32 v[110:111], v[32:33], v[122:123], v[110:111] op_sel:[0,1,0] op_sel_hi:[1,1,1]
	v_add_f32_dpp v132, v128, v128 row_ror:12 row_mask:0xf bank_mask:0x5 bound_ctrl:1
	v_pk_fma_f32 v[104:105], v[34:35], v[122:123], v[104:105] op_sel_hi:[1,0,1]
	v_pk_fma_f32 v[112:113], v[34:35], v[122:123], v[112:113] op_sel:[0,1,0] op_sel_hi:[1,1,1]
	v_add_f32_dpp v132, v129, v129 row_ror:4 row_mask:0xf bank_mask:0xa bound_ctrl:1
	v_pk_fma_f32 v[106:107], v[36:37], v[122:123], v[106:107] op_sel_hi:[1,0,1]
	v_pk_fma_f32 v[114:115], v[36:37], v[122:123], v[114:115] op_sel:[0,1,0] op_sel_hi:[1,1,1]
	v_add_f32_dpp v134, v130, v130 row_ror:12 row_mask:0xf bank_mask:0x5 bound_ctrl:1
	v_pk_fma_f32 v[108:109], v[38:39], v[122:123], v[108:109] op_sel_hi:[1,0,1]
	v_pk_fma_f32 v[116:117], v[38:39], v[122:123], v[116:117] op_sel:[0,1,0] op_sel_hi:[1,1,1]
	v_add_f32_dpp v134, v131, v131 row_ror:4 row_mask:0xf bank_mask:0xa bound_ctrl:1
	v_pk_fma_f32 v[0:1], v[0:1], v[40:41], v[102:103]
	v_pk_fma_f32 v[8:9], v[8:9], v[40:41], v[110:111]
	v_pk_fma_f32 v[2:3], v[2:3], v[42:43], v[104:105]
	v_pk_fma_f32 v[10:11], v[10:11], v[42:43], v[112:113]
	v_pk_fma_f32 v[4:5], v[4:5], v[44:45], v[106:107]
	v_pk_fma_f32 v[12:13], v[12:13], v[44:45], v[114:115]
	v_pk_fma_f32 v[6:7], v[6:7], v[46:47], v[108:109]
	v_pk_fma_f32 v[14:15], v[14:15], v[46:47], v[116:117]
	s_waitcnt lgkmcnt(9)
; DN void rw_scan_item(const Params& p, int l, int item, bool need_ctx, int mode) {
;     ...
;             for (int k = 0; k < 4; ++k) {
;               const f32x2 s2 = (f32x2){sa[k], sa[k]}, v2 = (f32x2){vi[k], vi[k]};
;               S[k][0] = S[k][0] * w0.xy + (s2 * b0.xy + v2 * d0.xy);
;               S[k][1] = S[k][1] * w0.zw + (s2 * b0.zw + v2 * d0.zw);
;               f32x2 y2 = S[k][0] * q0.xy;
;               y2 = S[k][1] * q0.zw + y2;
;               yp[k][s8] = y2.x + y2.y;
;             }
;           }
; #pragma unroll
;           for (int s8 = 0; s8 < 8; ++s8)
; #pragma unroll
;             for (int k = 0; k < 4; ++k) {
;               float ra = yp[k][s8];
;               ra += dppf<0xB1>(ra); ra += dppf<0x4E>(ra); ra += dppf<0x141>(ra); ra += dppf<0x140>(ra);
;               ykeep[k] = ((hb * 8 + s8) == j16) ? ra : ykeep[k];
;             }
;         }
; #pragma unroll
;         for (int k = 0; k < 4; ++k) ybuf[j16 * 64 + rq + 16 * k] = ykeep[k];
;       }
;       __syncthreads();
	v_pk_mul_f32 v[118:119], v[0:1], v[60:61]
	v_pk_mul_f32 v[120:121], v[8:9], v[60:61]
	v_pk_mul_f32 v[124:125], v[0:1], v[48:49]
	v_pk_fma_f32 v[118:119], v[2:3], v[62:63], v[118:119]
	v_pk_fma_f32 v[120:121], v[10:11], v[62:63], v[120:121]
	v_pk_mul_f32 v[126:127], v[8:9], v[48:49]
	v_pk_fma_f32 v[118:119], v[4:5], v[64:65], v[118:119]
	v_pk_fma_f32 v[120:121], v[12:13], v[64:65], v[120:121]
	v_pk_fma_f32 v[124:125], v[2:3], v[50:51], v[124:125]
	v_pk_fma_f32 v[118:119], v[6:7], v[66:67], v[118:119]
	v_pk_fma_f32 v[120:121], v[14:15], v[66:67], v[120:121]
	v_pk_fma_f32 v[126:127], v[10:11], v[50:51], v[126:127]
	v_add_f32_e32 v122, v118, v119
	v_add_f32_e32 v123, v120, v121
	v_pk_fma_f32 v[124:125], v[4:5], v[52:53], v[124:125]
	v_pk_fma_f32 v[126:127], v[12:13], v[52:53], v[126:127]
	v_add_f32_dpp v122, v122, v122 quad_perm:[1,0,3,2] row_mask:0xf bank_mask:0xf bound_ctrl:1
	v_add_f32_dpp v123, v123, v123 quad_perm:[1,0,3,2] row_mask:0xf bank_mask:0xf bound_ctrl:1
	v_pk_fma_f32 v[124:125], v[6:7], v[54:55], v[124:125]
	v_pk_fma_f32 v[126:127], v[14:15], v[54:55], v[126:127]
	v_add_f32_dpp v122, v122, v122 quad_perm:[2,3,0,1] row_mask:0xf bank_mask:0xf bound_ctrl:1
	v_add_f32_dpp v123, v123, v123 quad_perm:[2,3,0,1] row_mask:0xf bank_mask:0xf bound_ctrl:1
	v_add_f32_e32 v128, v124, v125
	v_add_f32_e32 v130, v126, v127
	v_add_f32_dpp v122, v122, v122 row_half_mirror row_mask:0xf bank_mask:0xf bound_ctrl:1
	v_add_f32_dpp v123, v123, v123 row_half_mirror row_mask:0xf bank_mask:0xf bound_ctrl:1
	s_waitcnt lgkmcnt(0)
	v_pk_mul_f32 v[102:103], v[68:69], v[100:101] op_sel_hi:[1,0]
	v_pk_mul_f32 v[110:111], v[68:69], v[100:101] op_sel:[0,1] op_sel_hi:[1,1]
	v_pk_mul_f32 v[104:105], v[70:71], v[100:101] op_sel_hi:[1,0]
	v_pk_mul_f32 v[112:113], v[70:71], v[100:101] op_sel:[0,1] op_sel_hi:[1,1]
	v_pk_mul_f32 v[106:107], v[72:73], v[100:101] op_sel_hi:[1,0]
	v_pk_mul_f32 v[114:115], v[72:73], v[100:101] op_sel:[0,1] op_sel_hi:[1,1]
	v_pk_mul_f32 v[108:109], v[74:75], v[100:101] op_sel_hi:[1,0]
	v_pk_mul_f32 v[116:117], v[74:75], v[100:101] op_sel:[0,1] op_sel_hi:[1,1]
	v_pk_fma_f32 v[102:103], v[76:77], v[122:123], v[102:103] op_sel_hi:[1,0,1]
	v_pk_fma_f32 v[110:111], v[76:77], v[122:123], v[110:111] op_sel:[0,1,0] op_sel_hi:[1,1,1]
	v_pk_fma_f32 v[104:105], v[78:79], v[122:123], v[104:105] op_sel_hi:[1,0,1]
	v_pk_fma_f32 v[112:113], v[78:79], v[122:123], v[112:113] op_sel:[0,1,0] op_sel_hi:[1,1,1]
	v_pk_fma_f32 v[106:107], v[80:81], v[122:123], v[106:107] op_sel_hi:[1,0,1]
	v_pk_fma_f32 v[114:115], v[80:81], v[122:123], v[114:115] op_sel:[0,1,0] op_sel_hi:[1,1,1]
	v_pk_fma_f32 v[108:109], v[82:83], v[122:123], v[108:109] op_sel_hi:[1,0,1]
	v_pk_fma_f32 v[116:117], v[82:83], v[122:123], v[116:117] op_sel:[0,1,0] op_sel_hi:[1,1,1]
	v_pk_fma_f32 v[0:1], v[0:1], v[84:85], v[102:103]
	v_pk_fma_f32 v[8:9], v[8:9], v[84:85], v[110:111]
	v_pk_fma_f32 v[2:3], v[2:3], v[86:87], v[104:105]
	v_pk_fma_f32 v[10:11], v[10:11], v[86:87], v[112:113]
	v_pk_fma_f32 v[4:5], v[4:5], v[88:89], v[106:107]
	v_pk_fma_f32 v[12:13], v[12:13], v[88:89], v[114:115]
	v_pk_fma_f32 v[6:7], v[6:7], v[90:91], v[108:109]
	v_pk_fma_f32 v[14:15], v[14:15], v[90:91], v[116:117]
	v_pk_mul_f32 v[124:125], v[0:1], v[92:93]
	v_pk_mul_f32 v[126:127], v[8:9], v[92:93]
	v_pk_fma_f32 v[124:125], v[2:3], v[94:95], v[124:125]
	v_pk_fma_f32 v[126:127], v[10:11], v[94:95], v[126:127]
	v_pk_fma_f32 v[124:125], v[4:5], v[96:97], v[124:125]
	v_pk_fma_f32 v[126:127], v[12:13], v[96:97], v[126:127]
	v_pk_fma_f32 v[124:125], v[6:7], v[98:99], v[124:125]
	v_pk_fma_f32 v[126:127], v[14:15], v[98:99], v[126:127]
	v_add_f32_e32 v129, v124, v125
	v_add_f32_e32 v131, v126, v127
	v_add_f32_dpp v133, v128, v128 row_ror:12 row_mask:0xf bank_mask:0x5 bound_ctrl:1
	v_add_f32_dpp v133, v129, v129 row_ror:4 row_mask:0xf bank_mask:0xa bound_ctrl:1
	v_add_f32_dpp v135, v130, v130 row_ror:12 row_mask:0xf bank_mask:0x5 bound_ctrl:1
	v_add_f32_dpp v135, v131, v131 row_ror:4 row_mask:0xf bank_mask:0xa bound_ctrl:1
	v_cndmask_b32_e64 v140, v132, v133, s[6:7]
	v_cndmask_b32_e64 v141, v133, v132, s[6:7]
	v_cndmask_b32_e64 v142, v134, v135, s[6:7]
	v_cndmask_b32_e64 v143, v135, v134, s[6:7]
	v_add_f32_dpp v137, v141, v140 quad_perm:[1,0,3,2] row_mask:0xf bank_mask:0xf bound_ctrl:1
	s_nop 0
	v_add_f32_dpp v139, v143, v142 quad_perm:[1,0,3,2] row_mask:0xf bank_mask:0xf bound_ctrl:1
	v_cndmask_b32_e64 v140, v136, v137, s[8:9]
	v_cndmask_b32_e64 v141, v137, v136, s[8:9]
	v_cndmask_b32_e64 v142, v138, v139, s[8:9]
	v_cndmask_b32_e64 v143, v139, v138, s[8:9]
	v_add_f32_dpp v146, v141, v140 quad_perm:[2,3,0,1] row_mask:0xf bank_mask:0xf bound_ctrl:1
	s_nop 0
	v_add_f32_dpp v147, v143, v142 quad_perm:[2,3,0,1] row_mask:0xf bank_mask:0xf bound_ctrl:1
	s_nop 0
	ds_write_b64 v148, v[144:145] offset:24576
	ds_write_b64 v148, v[146:147] offset:26624
	s_add_i32 s2, s2, 1
	s_cmpk_lt_i32 s2, 0x90
	s_waitcnt lgkmcnt(0)
	s_barrier
	s_cbranch_scc1 .Lrwc_chunk
	s_branch .LBB0_510
